# RWKV scan loop rewritten by hand (row-pair packed pk math, LDS operand prefetch one token ahead, setprio 2) + prep-wave vmcnt counted waits
# speedup vs baseline: 1.0099x; 1.0099x over previous
; #define LDS_BAR() do { asm volatile("s_waitcnt lgkmcnt(0)" ::: "memory"); __builtin_amdgcn_s_barrier(); asm volatile("" ::: "memory"); } while (0)
; __device__ __forceinline__ void rwkv_block(KP p, int o, int b, int hd, LAS unsigned char* lds, const bf16_t* P, bf16_t* YB) {
;     ...
;         for (int n = 0; n < 256; n += 2) {
;             if (n + 2 < 256) load_rows(n + 2, rawA);
;             if (n >= 1) outp(n - 1);
;             prep(n + 1, rawB);
;             LDS_BAR();
;             if (n + 3 < 256) load_rows(n + 3, rawB);
;             outp(n);
;             if (n + 2 < 256) prep(n + 2, rawA);
;             LDS_BAR();
.Lrk_noload_e:
	s_waitcnt vmcnt(0)
	s_branch .LBB0_206
.Lrk_first_e:
	s_waitcnt vmcnt(8)
	s_branch .LBB0_208

; #define LAS __attribute__((address_space(3)))
; __device__ __forceinline__ void rwkv_block(KP p, int o, int b, int hd, LAS unsigned char* lds, const bf16_t* P, bf16_t* YB) {
;     ...
;         auto prep = [&](int m, const Raw& d) {
;             LAS float* B = (LAS float*)(lds + BUF0 + (m & 1) * BUFSZ);
;             LAS float* Wd = B; LAS float* KK = B + 1024; LAS float* BB = B + 2048; LAS float* KM = B + 3072; LAS float* Rr = B + 4096; LAS float* Vv = B + 5120; LAS float* Gg = B + 6144; LAS float* Bon = B + 8192;
;             const int tt = 4 * q + t4;
;             f32x4 cv, pv;
;             cv = unpack4(d.r[1]); pv = unpack4(d.r[0]); const f32x4 rr = cv + mu_r * (pv - cv);
;             cv = unpack4(d.k[1]); pv = unpack4(d.k[0]); const f32x4 k0 = cv + mu_k * (pv - cv);
;             cv = unpack4(d.v[1]); pv = unpack4(d.v[0]); const f32x4 vv = cv + mu_v * (pv - cv);
;             {
;                 f32x4 la, lb;
;                 cv = unpack4((u32x2){d.l[1].x, d.l[1].y}); pv = unpack4((u32x2){d.l[0].x, d.l[0].y}); la = cv + mu_la * (pv - cv);
;                 cv = unpack4((u32x2){d.l[1].z, d.l[1].w}); pv = unpack4((u32x2){d.l[0].z, d.l[0].w}); lb = cv + mu_lb * (pv - cv);
;                 float o8[8];
; #pragma unroll
;                 for (int i = 0; i < 4; ++i) {
;                     const float sa = sigmoidf_(lsc * la[i]), sb = sigmoidf_(lsc * lb[i]);
;                     o8[i] = jg < 4 ? 2.0f * sa - 1.0f : (jg < 8 ? la[i] : sa);
;                     o8[4 + i] = jg < 4 ? 2.0f * sb - 1.0f : (jg < 8 ? lb[i] : sb);
;                 }
;                 u32x4 w; w.x = pk2(o8[0], o8[1]); w.y = pk2(o8[2], o8[3]); w.z = pk2(o8[4], o8[5]); w.w = pk2(o8[6], o8[7]);
;                 *(LAS u32x4*)(Lin + t4 * 136 + 8 * jg) = w;
;             }
;             LDS_WAIT(); asm volatile("" ::: "memory");
; #pragma unroll
;             for (int ct = 0; ct < 4; ++ct) {
;                 f32x4 c0 = {0.f, 0.f, 0.f, 0.f}, c1 = {0.f, 0.f, 0.f, 0.f}, c2 = {0.f, 0.f, 0.f, 0.f};
;                 c0 = mfma16(*(const LAS bf16x8*)(Lin + fr * 136 + fq * 8), *(const LAS bf16x8*)(wBt + (ct * 16 + fr) * 40 + fq * 8), c0);
;                 c1 = mfma16(*(const LAS bf16x8*)(Lin + fr * 136 + 32 + fq * 8), *(const LAS bf16x8*)(aBt + (ct * 16 + fr) * 40 + fq * 8), c1);
; #pragma unroll
;                 for (int kb = 0; kb < 2; ++kb)
.LBB0_208:
	s_waitcnt vmcnt(9)
	v_lshlrev_b32_e32 v0, 16, v60
	v_lshlrev_b32_e32 v70, 16, v64
	v_lshlrev_b32_e32 v74, 16, v62
	v_lshlrev_b32_e32 v78, 16, v66
	v_sub_f32_e32 v70, v70, v0
	v_sub_f32_e32 v78, v78, v74
	v_fmac_f32_e32 v0, v16, v70
	v_fmac_f32_e32 v74, v28, v78
	v_mul_f32_e32 v70, v103, v0
	v_mul_f32_e32 v78, v103, v74
	v_mul_f32_e32 v70, 0xbfb8aa3b, v70
	v_mul_f32_e32 v78, 0xbfb8aa3b, v78
	v_exp_f32_e32 v70, v70
	v_exp_f32_e32 v78, v78
	v_and_b32_e32 v3, 0xffff0000, v60
	v_and_b32_e32 v71, 0xffff0000, v64
	v_add_f32_e32 v70, 1.0, v70
	v_add_f32_e32 v78, 1.0, v78
	v_rcp_f32_e32 v70, v70
	v_rcp_f32_e32 v78, v78
	v_and_b32_e32 v75, 0xffff0000, v62
	v_and_b32_e32 v79, 0xffff0000, v66
	v_sub_f32_e32 v71, v71, v3
	v_sub_f32_e32 v79, v79, v75
	v_fmac_f32_e32 v3, v17, v71
	v_fmac_f32_e32 v75, v29, v79
	v_fma_f32 v82, v70, 2.0, -1.0
	v_cndmask_b32_e64 v0, v70, v0, s[12:13]
	v_fma_f32 v70, v78, 2.0, -1.0
	v_cndmask_b32_e64 v74, v78, v74, s[12:13]
	v_mul_f32_e32 v71, v103, v3
	v_mul_f32_e32 v78, v103, v75
	v_mul_f32_e32 v71, 0xbfb8aa3b, v71
	v_mul_f32_e32 v78, 0xbfb8aa3b, v78
	v_exp_f32_e32 v71, v71
	v_exp_f32_e32 v78, v78
	v_lshlrev_b32_e32 v68, 16, v61
	v_lshlrev_b32_e32 v72, 16, v65
	v_sub_f32_e32 v72, v72, v68
	v_fmac_f32_e32 v68, v18, v72
	v_add_f32_e32 v71, 1.0, v71
	v_cndmask_b32_e64 v70, v74, v70, s[10:11]
	v_add_f32_e32 v74, 1.0, v78
	v_mul_f32_e32 v72, v103, v68
	v_rcp_f32_e32 v71, v71
	v_rcp_f32_e32 v74, v74
	v_mul_f32_e32 v72, 0xbfb8aa3b, v72
	v_lshlrev_b32_e32 v76, 16, v63
	v_lshlrev_b32_e32 v80, 16, v67
	v_exp_f32_e32 v72, v72
	v_sub_f32_e32 v80, v80, v76
	v_fmac_f32_e32 v76, v30, v80
	v_fma_f32 v78, v71, 2.0, -1.0
	v_cndmask_b32_e64 v3, v71, v3, s[12:13]
	v_fma_f32 v71, v74, 2.0, -1.0
	v_cndmask_b32_e64 v74, v74, v75, s[12:13]
	v_mul_f32_e32 v75, v103, v76
	v_mul_f32_e32 v75, 0xbfb8aa3b, v75
	v_add_f32_e32 v72, 1.0, v72
	v_exp_f32_e32 v75, v75
	v_rcp_f32_e32 v72, v72
	v_and_b32_e32 v69, 0xffff0000, v61
	v_and_b32_e32 v73, 0xffff0000, v65
	v_and_b32_e32 v77, 0xffff0000, v63
	v_and_b32_e32 v81, 0xffff0000, v67
	v_sub_f32_e32 v73, v73, v69
	v_sub_f32_e32 v81, v81, v77
	v_cndmask_b32_e64 v71, v74, v71, s[10:11]
	v_add_f32_e32 v74, 1.0, v75
	v_fma_f32 v75, v72, 2.0, -1.0
	v_cndmask_b32_e64 v68, v72, v68, s[12:13]
	v_fmac_f32_e32 v69, v19, v73
	v_fmac_f32_e32 v77, v31, v81
	v_cndmask_b32_e64 v72, v68, v75, s[10:11]
	v_mul_f32_e32 v73, v103, v69
	v_mul_f32_e32 v75, v103, v77
	v_rcp_f32_e32 v74, v74
	v_mul_f32_e32 v73, 0xbfb8aa3b, v73
	v_mul_f32_e32 v75, 0xbfb8aa3b, v75
	v_exp_f32_e32 v73, v73
	v_exp_f32_e32 v75, v75
	v_fma_f32 v68, v74, 2.0, -1.0
	v_cndmask_b32_e64 v74, v74, v76, s[12:13]
	v_add_f32_e32 v73, 1.0, v73
	v_cndmask_b32_e64 v74, v74, v68, s[10:11]
	v_add_f32_e32 v68, 1.0, v75
	v_rcp_f32_e32 v73, v73
	v_rcp_f32_e32 v68, v68
	v_cndmask_b32_e64 v0, v0, v82, s[10:11]
	v_cndmask_b32_e64 v3, v3, v78, s[10:11]
	v_fma_f32 v75, v73, 2.0, -1.0
	v_cndmask_b32_e64 v69, v73, v69, s[12:13]
	v_fma_f32 v73, v68, 2.0, -1.0
	v_cndmask_b32_e64 v68, v68, v77, s[12:13]
	v_cndmask_b32_e64 v69, v69, v75, s[10:11]
	v_cndmask_b32_e64 v73, v68, v73, s[10:11]
	v_cvt_pk_bf16_f32 v68, v0, v3
	v_cvt_pk_bf16_f32 v69, v72, v69
	v_cvt_pk_bf16_f32 v70, v70, v71
	v_cvt_pk_bf16_f32 v71, v74, v73
	ds_write_b128 v132, v[68:71] offset:19456
	s_waitcnt lgkmcnt(0)
	ds_read_b128 v[80:83], v133 offset:19584
	ds_read_b128 v[76:79], v133 offset:19648
	ds_read_b128 v[68:71], v163 offset:10240
	ds_read_b128 v[84:87], v163 offset:10304
	s_waitcnt lgkmcnt(1)
	v_mfma_f32_16x16x32_bf16 v[88:91], v[80:83], v[68:71], 0
	ds_read_b128 v[72:75], v133 offset:19456
	ds_read_b128 v[68:71], v133 offset:19520
	s_waitcnt lgkmcnt(2)
	v_mfma_f32_16x16x32_bf16 v[84:87], v[76:79], v[84:87], v[88:91]
	s_nop 3
	ds_read_b128 v[88:91], v162
	ds_read_b128 v[92:95], v162 offset:5120
	s_waitcnt lgkmcnt(1)
	v_mfma_f32_16x16x32_bf16 v[88:91], v[72:75], v[88:91], 0
	s_waitcnt lgkmcnt(0)
	v_mfma_f32_16x16x32_bf16 v[92:95], v[68:71], v[92:95], 0
	s_and_saveexec_b64 s[18:19], s[14:15]
	s_cbranch_execz .LBB0_210
	s_nop 3
	ds_write2_b32 v134, v88, v89 offset1:68
	s_nop 0
	ds_write2_b32 v135, v92, v93 offset0:16 offset1:84
	ds_write2_b32 v136, v84, v85 offset0:32 offset1:100
	ds_write2_b32 v134, v90, v91 offset0:136 offset1:204
	ds_write2_b32 v135, v94, v95 offset0:152 offset1:220
	ds_write2_b32 v136, v86, v87 offset0:168 offset1:236
	ds_read_b128 v[72:75], v133 offset:19456
	ds_read_b128 v[68:71], v133 offset:19520
	ds_read_b128 v[80:83], v133 offset:19584
	ds_read_b128 v[76:79], v133 offset:19648

; #define LAS __attribute__((address_space(3)))
; __device__ __forceinline__ void rwkv_block(KP p, int o, int b, int hd, LAS unsigned char* lds, const bf16_t* P, bf16_t* YB) {
;     ...
;             const int tt = 4 * q + t4;
;             f32x4 cv, pv;
;             cv = unpack4(d.r[1]); pv = unpack4(d.r[0]); const f32x4 rr = cv + mu_r * (pv - cv);
;             cv = unpack4(d.k[1]); pv = unpack4(d.k[0]); const f32x4 k0 = cv + mu_k * (pv - cv);
;             cv = unpack4(d.v[1]); pv = unpack4(d.v[0]); const f32x4 vv = cv + mu_v * (pv - cv);
;             {
;                 f32x4 la, lb;
;                 cv = unpack4((u32x2){d.l[1].x, d.l[1].y}); pv = unpack4((u32x2){d.l[0].x, d.l[0].y}); la = cv + mu_la * (pv - cv);
;                 cv = unpack4((u32x2){d.l[1].z, d.l[1].w}); pv = unpack4((u32x2){d.l[0].z, d.l[0].w}); lb = cv + mu_lb * (pv - cv);
;                 float o8[8];
; #pragma unroll
;                 for (int i = 0; i < 4; ++i) {
;                     const float sa = sigmoidf_(lsc * la[i]), sb = sigmoidf_(lsc * lb[i]);
;                     o8[i] = jg < 4 ? 2.0f * sa - 1.0f : (jg < 8 ? la[i] : sa);
;                     o8[4 + i] = jg < 4 ? 2.0f * sb - 1.0f : (jg < 8 ? lb[i] : sb);
;                 }
;                 u32x4 w; w.x = pk2(o8[0], o8[1]); w.y = pk2(o8[2], o8[3]); w.z = pk2(o8[4], o8[5]); w.w = pk2(o8[6], o8[7]);
;                 *(LAS u32x4*)(Lin + t4 * 136 + 8 * jg) = w;
;             }
;             LDS_WAIT(); asm volatile("" ::: "memory");
; #pragma unroll
;             for (int ct = 0; ct < 4; ++ct) {
;                 f32x4 c0 = {0.f, 0.f, 0.f, 0.f}, c1 = {0.f, 0.f, 0.f, 0.f}, c2 = {0.f, 0.f, 0.f, 0.f};
;     ...
;             const f32x4 y = *(const LAS f32x4*)(Yy + tt * 64 + 4 * jg);
;             const float mean = red16((y.x + y.y) + (y.z + y.w)) * (1.f / 64.f);
;             const f32x4 dd = y - mean;
;             const float var = red16((dd.x * dd.x + dd.y * dd.y) + (dd.z * dd.z + dd.w * dd.w)) * (1.f / 64.f);
;             const f32x4 yn = dd * __builtin_amdgcn_rsqf(var + 64e-5f) * lng + lnb;
;             const f32x4 ov = (yn + Bon[tt] * *(const LAS f32x4*)(Vv + tt * 64 + 4 * jg)) * *(const LAS f32x4*)(Gg + tt * 64 + 4 * jg);
;             u32x2 w; w.x = pk2(ov.x, ov.y); w.y = pk2(ov.z, ov.w);
;             *(u32x2*)(YB + row * DM + ch0) = w;
;             LDS_WAIT(); asm volatile("" ::: "memory");
.LBB0_220:
	ds_read_b128 v[68:71], v161
	s_andn2_b64 vcc, exec, s[26:27]
	s_waitcnt lgkmcnt(0)
	v_mov_b32_e32 v72, v69
	v_mov_b32_e32 v73, v70
	v_mov_b32_e32 v74, v68
	v_mov_b32_e32 v75, v71
	v_pk_add_f32 v[72:73], v[72:73], v[74:75]
	s_nop 0
	v_add_f32_e32 v0, v72, v73
	s_nop 1
	v_add_f32_dpp v0, v0, v0 quad_perm:[1,0,3,2] row_mask:0xf bank_mask:0xf bound_ctrl:1
	s_nop 1
	v_add_f32_dpp v0, v0, v0 quad_perm:[2,3,0,1] row_mask:0xf bank_mask:0xf bound_ctrl:1
	s_nop 1
	v_add_f32_dpp v0, v0, v0 row_half_mirror row_mask:0xf bank_mask:0xf bound_ctrl:1
	s_nop 1
	v_add_f32_dpp v0, v0, v0 row_mirror row_mask:0xf bank_mask:0xf bound_ctrl:1
	v_fmamk_f32 v69, v0, 0xbc800000, v69
	v_fmamk_f32 v68, v0, 0xbc800000, v68
	v_fmamk_f32 v71, v0, 0xbc800000, v71
	v_fmac_f32_e32 v70, 0xbc800000, v0
	v_pk_mul_f32 v[72:73], v[70:71], v[70:71]
	v_pk_mul_f32 v[74:75], v[68:69], v[68:69]
	s_nop 0
	v_pk_mov_b32 v[76:77], v[74:75], v[72:73] op_sel:[1,0]
	v_mov_b32_e32 v75, v73
	v_pk_add_f32 v[72:73], v[76:77], v[74:75]
	s_nop 0
	v_add_f32_e32 v0, v72, v73
	s_nop 1
	v_add_f32_dpp v0, v0, v0 quad_perm:[1,0,3,2] row_mask:0xf bank_mask:0xf bound_ctrl:1
	s_nop 1
	v_add_f32_dpp v0, v0, v0 quad_perm:[2,3,0,1] row_mask:0xf bank_mask:0xf bound_ctrl:1
	s_nop 1
	v_add_f32_dpp v0, v0, v0 row_half_mirror row_mask:0xf bank_mask:0xf bound_ctrl:1
	s_nop 1
	v_add_f32_dpp v0, v0, v0 row_mirror row_mask:0xf bank_mask:0xf bound_ctrl:1
	v_fmamk_f32 v0, v0, 0x3c800000, v227
	v_rsq_f32_e32 v0, v0
	s_nop 0
	v_pk_mul_f32 v[68:69], v[68:69], v[0:1] op_sel_hi:[1,0]
	v_pk_mul_f32 v[70:71], v[70:71], v[0:1] op_sel_hi:[1,0]
	v_pk_fma_f32 v[74:75], v[12:13], v[68:69], v[20:21]
	v_pk_fma_f32 v[72:73], v[14:15], v[70:71], v[22:23]
	ds_read_b32 v0, v152
	ds_read_b128 v[68:71], v153
	s_waitcnt lgkmcnt(0)
	v_pk_fma_f32 v[74:75], v[68:69], v[0:1], v[74:75] op_sel_hi:[1,0,1]
	v_pk_fma_f32 v[72:73], v[70:71], v[0:1], v[72:73] op_sel_hi:[1,0,1]
	ds_read_b128 v[68:71], v154
	s_waitcnt lgkmcnt(0)
	v_pk_mul_f32 v[70:71], v[70:71], v[72:73]
	v_pk_mul_f32 v[68:69], v[68:69], v[74:75]
	s_nop 0
	v_cvt_pk_bf16_f32 v68, v68, v69
	v_cvt_pk_bf16_f32 v69, v70, v71
	global_store_dwordx2 v[130:131], v[68:69], off
	s_waitcnt lgkmcnt(0)
	s_cbranch_vccnz .LBB0_203
	s_waitcnt vmcnt(9)
	v_lshlrev_b32_e32 v0, 16, v52
	v_lshlrev_b32_e32 v70, 16, v56
	v_lshlrev_b32_e32 v74, 16, v54
	v_lshlrev_b32_e32 v78, 16, v58
	v_sub_f32_e32 v70, v70, v0
	v_sub_f32_e32 v78, v78, v74
	v_fmac_f32_e32 v0, v16, v70
	v_fmac_f32_e32 v74, v28, v78
	v_mul_f32_e32 v70, v103, v0
	v_mul_f32_e32 v78, v103, v74
	v_mul_f32_e32 v70, 0xbfb8aa3b, v70
	v_mul_f32_e32 v78, 0xbfb8aa3b, v78
	v_exp_f32_e32 v70, v70
	v_exp_f32_e32 v78, v78
	v_and_b32_e32 v3, 0xffff0000, v52
	v_and_b32_e32 v71, 0xffff0000, v56
	v_add_f32_e32 v70, 1.0, v70
	v_add_f32_e32 v78, 1.0, v78
	v_rcp_f32_e32 v70, v70
	v_rcp_f32_e32 v78, v78
	v_and_b32_e32 v75, 0xffff0000, v54
	v_and_b32_e32 v79, 0xffff0000, v58
	v_sub_f32_e32 v71, v71, v3
	v_sub_f32_e32 v79, v79, v75
	v_fmac_f32_e32 v3, v17, v71
	v_fmac_f32_e32 v75, v29, v79
	v_fma_f32 v82, v70, 2.0, -1.0
	v_cndmask_b32_e64 v0, v70, v0, s[12:13]
	v_fma_f32 v70, v78, 2.0, -1.0
	v_cndmask_b32_e64 v74, v78, v74, s[12:13]
	v_mul_f32_e32 v71, v103, v3
	v_mul_f32_e32 v78, v103, v75
	v_mul_f32_e32 v71, 0xbfb8aa3b, v71
	v_mul_f32_e32 v78, 0xbfb8aa3b, v78
	v_exp_f32_e32 v71, v71
	v_exp_f32_e32 v78, v78
	v_lshlrev_b32_e32 v68, 16, v53
	v_lshlrev_b32_e32 v72, 16, v57
	v_sub_f32_e32 v72, v72, v68
	v_fmac_f32_e32 v68, v18, v72
	v_add_f32_e32 v71, 1.0, v71
	v_cndmask_b32_e64 v70, v74, v70, s[10:11]
	v_add_f32_e32 v74, 1.0, v78
	v_mul_f32_e32 v72, v103, v68
	v_rcp_f32_e32 v71, v71
	v_rcp_f32_e32 v74, v74
	v_mul_f32_e32 v72, 0xbfb8aa3b, v72
	v_lshlrev_b32_e32 v76, 16, v55
	v_lshlrev_b32_e32 v80, 16, v59
	v_exp_f32_e32 v72, v72
	v_sub_f32_e32 v80, v80, v76
	v_fmac_f32_e32 v76, v30, v80
	v_fma_f32 v78, v71, 2.0, -1.0
	v_cndmask_b32_e64 v3, v71, v3, s[12:13]
	v_fma_f32 v71, v74, 2.0, -1.0
	v_cndmask_b32_e64 v74, v74, v75, s[12:13]
	v_mul_f32_e32 v75, v103, v76
	v_mul_f32_e32 v75, 0xbfb8aa3b, v75
	v_add_f32_e32 v72, 1.0, v72
	v_exp_f32_e32 v75, v75
	v_rcp_f32_e32 v72, v72
	v_and_b32_e32 v69, 0xffff0000, v53
	v_and_b32_e32 v73, 0xffff0000, v57
	v_and_b32_e32 v77, 0xffff0000, v55
	v_and_b32_e32 v81, 0xffff0000, v59
	v_sub_f32_e32 v73, v73, v69
	v_sub_f32_e32 v81, v81, v77
	v_cndmask_b32_e64 v71, v74, v71, s[10:11]
	v_add_f32_e32 v74, 1.0, v75
	v_fma_f32 v75, v72, 2.0, -1.0
	v_cndmask_b32_e64 v68, v72, v68, s[12:13]
	v_fmac_f32_e32 v69, v19, v73
	v_fmac_f32_e32 v77, v31, v81
	v_cndmask_b32_e64 v72, v68, v75, s[10:11]
	v_mul_f32_e32 v73, v103, v69
	v_mul_f32_e32 v75, v103, v77
	v_rcp_f32_e32 v74, v74
	v_mul_f32_e32 v73, 0xbfb8aa3b, v73
	v_mul_f32_e32 v75, 0xbfb8aa3b, v75
	v_exp_f32_e32 v73, v73
	v_exp_f32_e32 v75, v75
	v_fma_f32 v68, v74, 2.0, -1.0
	v_cndmask_b32_e64 v74, v74, v76, s[12:13]
	v_add_f32_e32 v73, 1.0, v73
	v_cndmask_b32_e64 v74, v74, v68, s[10:11]
	v_add_f32_e32 v68, 1.0, v75
	v_rcp_f32_e32 v73, v73
	v_rcp_f32_e32 v68, v68
	v_cndmask_b32_e64 v0, v0, v82, s[10:11]
	v_cndmask_b32_e64 v3, v3, v78, s[10:11]
	v_fma_f32 v75, v73, 2.0, -1.0
	v_cndmask_b32_e64 v69, v73, v69, s[12:13]
	v_fma_f32 v73, v68, 2.0, -1.0
	v_cndmask_b32_e64 v68, v68, v77, s[12:13]
	v_cndmask_b32_e64 v69, v69, v75, s[10:11]
	v_cndmask_b32_e64 v73, v68, v73, s[10:11]
	v_cvt_pk_bf16_f32 v68, v0, v3
	v_cvt_pk_bf16_f32 v69, v72, v69
	v_cvt_pk_bf16_f32 v70, v70, v71
	v_cvt_pk_bf16_f32 v71, v74, v73
	ds_write_b128 v132, v[68:71] offset:19456
	s_waitcnt lgkmcnt(0)
	ds_read_b128 v[80:83], v133 offset:19584
	ds_read_b128 v[76:79], v133 offset:19648
	ds_read_b128 v[68:71], v163 offset:10240
	ds_read_b128 v[84:87], v163 offset:10304
	s_waitcnt lgkmcnt(1)
	v_mfma_f32_16x16x32_bf16 v[88:91], v[80:83], v[68:71], 0
	ds_read_b128 v[72:75], v133 offset:19456
	ds_read_b128 v[68:71], v133 offset:19520
	s_waitcnt lgkmcnt(2)
	v_mfma_f32_16x16x32_bf16 v[84:87], v[76:79], v[84:87], v[88:91]
	s_nop 3
	ds_read_b128 v[88:91], v162
	ds_read_b128 v[92:95], v162 offset:5120
	s_waitcnt lgkmcnt(1)
	v_mfma_f32_16x16x32_bf16 v[88:91], v[72:75], v[88:91], 0
	s_waitcnt lgkmcnt(0)
	v_mfma_f32_16x16x32_bf16 v[92:95], v[68:71], v[92:95], 0
	s_and_saveexec_b64 s[18:19], s[14:15]
	s_cbranch_execz .LBB0_223
	s_nop 3
	ds_write2_b32 v134, v88, v89 offset1:68
	s_nop 0
	ds_write2_b32 v135, v92, v93 offset0:16 offset1:84
	ds_write2_b32 v136, v84, v85 offset0:32 offset1:100
	ds_write2_b32 v134, v90, v91 offset0:136 offset1:204
	ds_write2_b32 v135, v94, v95 offset0:152 offset1:220
	ds_write2_b32 v136, v86, v87 offset0:168 offset1:236
	ds_read_b128 v[72:75], v133 offset:19456
	ds_read_b128 v[68:71], v133 offset:19520
	ds_read_b128 v[80:83], v133 offset:19584
	ds_read_b128 v[76:79], v133 offset:19648

; #define LAS __attribute__((address_space(3)))
; __device__ __forceinline__ void rwkv_block(KP p, int o, int b, int hd, LAS unsigned char* lds, const bf16_t* P, bf16_t* YB) {
;     ...
; #pragma unroll 1
;         for (int n = 0; n < 256; ++n) {
;             LAS float* B = (LAS float*)(lds + BUF0 + (n & 1) * BUFSZ);
;             LAS float* Wd = B; LAS float* KK = B + 1024; LAS float* BB = B + 2048; LAS float* KM = B + 3072; LAS float* Rr = B + 4096; LAS float* Vv = B + 5120; LAS float* Yy = B + 7168;
;             f32x2 sv[2][4];
; #pragma unroll
;             for (int a = 0; a < 2; ++a)
; #pragma unroll
;                 for (int j = 0; j < 4; ++j) sv[a][j] = s[a][j];
; #pragma unroll 1
;             for (int rep2 = 0; rep2 < ((DUP_MASK & 128) ? 2 : 1); ++rep2) {
;             if (rep2 == 1) {
; #pragma unroll
;                 for (int a = 0; a < 2; ++a)
; #pragma unroll
;                     for (int j = 0; j < 4; ++j) s[a][j] = sv[a][j];
;             }
; #pragma unroll
;             for (int tt = 0; tt < 16; ++tt) {
;                 const int o8 = tt * 64 + c * 8;
;                 const f32x4 ka = *(const LAS f32x4*)(KK + o8), kb = *(const LAS f32x4*)(KK + o8 + 4);
;                 const f32x4 wa = *(const LAS f32x4*)(Wd + o8), wb = *(const LAS f32x4*)(Wd + o8 + 4);
;                 const f32x4 ba = *(const LAS f32x4*)(BB + o8), bb = *(const LAS f32x4*)(BB + o8 + 4);
;                 const f32x4 ma = *(const LAS f32x4*)(KM + o8), mb = *(const LAS f32x4*)(KM + o8 + 4);
;                 const f32x4 ra = *(const LAS f32x4*)(Rr + o8), rb = *(const LAS f32x4*)(Rr + o8 + 4);
;                 const f32x2 v01 = *(const LAS f32x2*)(Vv + tt * 64 + 2 * rp);
;                 const f32x2 k2[4] = {{ka[0], ka[1]}, {ka[2], ka[3]}, {kb[0], kb[1]}, {kb[2], kb[3]}};
;                 const f32x2 w2[4] = {{wa[0], wa[1]}, {wa[2], wa[3]}, {wb[0], wb[1]}, {wb[2], wb[3]}};
;                 const f32x2 b2[4] = {{ba[0], ba[1]}, {ba[2], ba[3]}, {bb[0], bb[1]}, {bb[2], bb[3]}};
;                 const f32x2 m2[4] = {{ma[0], ma[1]}, {ma[2], ma[3]}, {mb[0], mb[1]}, {mb[2], mb[3]}};
;                 const f32x2 r2[4] = {{ra[0], ra[1]}, {ra[2], ra[3]}, {rb[0], rb[1]}, {rb[2], rb[3]}};
;                 f32x2 accA = s[0][0] * k2[0], accB = s[1][0] * k2[0], accA2 = s[0][2] * k2[2], accB2 = s[1][2] * k2[2];
.LBB0_232:
	s_andn2_saveexec_b64 s[10:11], s[20:21]
	s_cbranch_execz .LBB0_156
	v_and_b32_e32 v3, 7, v2
	s_waitcnt lgkmcnt(0)
	s_barrier
	s_setprio 2
	v_ashrrev_i32_e32 v2, 2, v2
	v_lshlrev_b32_e32 v182, 5, v3
	v_and_b32_e32 v2, -2, v2
	v_lshlrev_b32_e32 v183, 2, v2
	v_cmp_eq_u32_e32 vcc, 0, v3
	s_mov_b64 s[12:13], exec
	s_mov_b32 s1, 0
	v_mov_b32_e32 v2, 0
	v_mov_b32_e32 v3, 0
	v_mov_b32_e32 v4, 0
	v_mov_b32_e32 v5, 0
	v_mov_b32_e32 v6, 0
	v_mov_b32_e32 v7, 0
	v_mov_b32_e32 v8, 0
	v_mov_b32_e32 v9, 0
	v_mov_b32_e32 v10, 0
	v_mov_b32_e32 v11, 0
	v_mov_b32_e32 v12, 0
	v_mov_b32_e32 v13, 0
	v_mov_b32_e32 v14, 0
	v_mov_b32_e32 v15, 0
	v_mov_b32_e32 v16, 0
	v_mov_b32_e32 v17, 0
.Lrk_scan_loop:
	s_bitcmp1_b32 s1, 0
	s_cselect_b32 s7, 0x8040, 0
	s_add_i32 s7, s7, 0xc300
	v_add_u32_e32 v180, s7, v182
	v_add_u32_e32 v181, s7, v183
	ds_read_b128 v[64:67], v180 offset:4096
	ds_read_b128 v[68:71], v180 offset:4112
	ds_read_b64 v[104:105], v181 offset:20480
	ds_read_b128 v[88:91], v180 offset:12288
	ds_read_b128 v[92:95], v180 offset:12304
	ds_read_b128 v[72:75], v180 offset:0
	ds_read_b128 v[76:79], v180 offset:16
	ds_read_b128 v[80:83], v180 offset:8192
	ds_read_b128 v[84:87], v180 offset:8208
	ds_read_b128 v[96:99], v180 offset:16384
	ds_read_b128 v[100:103], v180 offset:16400
	ds_read_b128 v[110:113], v180 offset:4352
	ds_read_b128 v[114:117], v180 offset:4368
	ds_read_b64 v[150:151], v181 offset:20736
	ds_read_b128 v[134:137], v180 offset:12544
	s_waitcnt lgkmcnt(4)
	ds_read_b128 v[138:141], v180 offset:12560
	ds_read_b128 v[118:121], v180 offset:256
	ds_read_b128 v[122:125], v180 offset:272
	ds_read_b128 v[126:129], v180 offset:8448
	ds_read_b128 v[130:133], v180 offset:8464
	ds_read_b128 v[142:145], v180 offset:16640
	ds_read_b128 v[146:149], v180 offset:16656
	v_pk_mul_f32 v[20:21], v[2:3], v[64:65] op_sel_hi:[1,0]
	v_pk_mul_f32 v[22:23], v[10:11], v[68:69] op_sel_hi:[1,0]
	v_pk_fma_f32 v[20:21], v[4:5], v[64:65], v[20:21] op_sel:[0,1,0]
	v_pk_fma_f32 v[22:23], v[12:13], v[68:69], v[22:23] op_sel:[0,1,0]
	v_pk_fma_f32 v[20:21], v[6:7], v[66:67], v[20:21] op_sel_hi:[1,0,1]
	v_pk_fma_f32 v[22:23], v[14:15], v[70:71], v[22:23] op_sel_hi:[1,0,1]
	v_pk_fma_f32 v[20:21], v[8:9], v[66:67], v[20:21] op_sel:[0,1,0]
	v_pk_fma_f32 v[22:23], v[16:17], v[70:71], v[22:23] op_sel:[0,1,0]
	v_pk_mul_f32 v[24:25], v[104:105], v[88:89] op_sel_hi:[1,0]
	v_pk_add_f32 v[20:21], v[20:21], v[22:23]
	v_pk_fma_f32 v[24:25], v[2:3], v[72:73], v[24:25] op_sel_hi:[1,0,1]
	v_pk_mul_f32 v[26:27], v[104:105], v[88:89] op_sel:[0,1]
	v_add_f32_dpp v20, v20, v20 quad_perm:[1,0,3,2] row_mask:0xf bank_mask:0xf bound_ctrl:1
	v_add_f32_dpp v21, v21, v21 quad_perm:[1,0,3,2] row_mask:0xf bank_mask:0xf bound_ctrl:1
	v_pk_fma_f32 v[26:27], v[4:5], v[72:73], v[26:27] op_sel:[0,1,0]
	v_add_f32_dpp v20, v20, v20 quad_perm:[2,3,0,1] row_mask:0xf bank_mask:0xf bound_ctrl:1
	v_add_f32_dpp v21, v21, v21 quad_perm:[2,3,0,1] row_mask:0xf bank_mask:0xf bound_ctrl:1
	v_pk_mul_f32 v[28:29], v[104:105], v[90:91] op_sel_hi:[1,0]
	v_add_f32_dpp v20, v20, v20 row_half_mirror row_mask:0xf bank_mask:0xf bound_ctrl:1
	v_add_f32_dpp v21, v21, v21 row_half_mirror row_mask:0xf bank_mask:0xf bound_ctrl:1
	v_pk_fma_f32 v[28:29], v[6:7], v[74:75], v[28:29] op_sel_hi:[1,0,1]
	v_pk_fma_f32 v[2:3], v[20:21], v[80:81], v[24:25] op_sel_hi:[1,0,1]
	v_pk_fma_f32 v[4:5], v[20:21], v[80:81], v[26:27] op_sel:[0,1,0]
	v_pk_fma_f32 v[6:7], v[20:21], v[82:83], v[28:29] op_sel_hi:[1,0,1]
	v_pk_mul_f32 v[30:31], v[104:105], v[90:91] op_sel:[0,1]
	v_pk_mul_f32 v[32:33], v[104:105], v[92:93] op_sel_hi:[1,0]
	v_pk_fma_f32 v[30:31], v[8:9], v[74:75], v[30:31] op_sel:[0,1,0]
	v_pk_fma_f32 v[32:33], v[10:11], v[76:77], v[32:33] op_sel_hi:[1,0,1]
	v_pk_fma_f32 v[8:9], v[20:21], v[82:83], v[30:31] op_sel:[0,1,0]
	v_pk_fma_f32 v[10:11], v[20:21], v[84:85], v[32:33] op_sel_hi:[1,0,1]
	v_pk_mul_f32 v[34:35], v[104:105], v[92:93] op_sel:[0,1]
	v_pk_mul_f32 v[36:37], v[104:105], v[94:95] op_sel_hi:[1,0]
	v_pk_fma_f32 v[34:35], v[12:13], v[76:77], v[34:35] op_sel:[0,1,0]
	v_pk_fma_f32 v[36:37], v[14:15], v[78:79], v[36:37] op_sel_hi:[1,0,1]
	v_pk_fma_f32 v[12:13], v[20:21], v[84:85], v[34:35] op_sel:[0,1,0]
	v_pk_fma_f32 v[14:15], v[20:21], v[86:87], v[36:37] op_sel_hi:[1,0,1]
	v_pk_mul_f32 v[38:39], v[104:105], v[94:95] op_sel:[0,1]
	v_pk_mul_f32 v[40:41], v[2:3], v[96:97] op_sel_hi:[1,0]
	v_pk_fma_f32 v[38:39], v[16:17], v[78:79], v[38:39] op_sel:[0,1,0]
	v_pk_mul_f32 v[44:45], v[10:11], v[100:101] op_sel_hi:[1,0]
	v_pk_fma_f32 v[16:17], v[20:21], v[86:87], v[38:39] op_sel:[0,1,0]
	v_pk_fma_f32 v[40:41], v[4:5], v[96:97], v[40:41] op_sel:[0,1,0]
	v_pk_fma_f32 v[44:45], v[12:13], v[100:101], v[44:45] op_sel:[0,1,0]
	v_pk_fma_f32 v[40:41], v[6:7], v[98:99], v[40:41] op_sel_hi:[1,0,1]
	v_pk_fma_f32 v[44:45], v[14:15], v[102:103], v[44:45] op_sel_hi:[1,0,1]
	v_pk_fma_f32 v[40:41], v[8:9], v[98:99], v[40:41] op_sel:[0,1,0]
	v_pk_fma_f32 v[44:45], v[16:17], v[102:103], v[44:45] op_sel:[0,1,0]
	v_pk_add_f32 v[40:41], v[40:41], v[44:45]
	ds_read_b128 v[64:67], v180 offset:4608
	ds_read_b128 v[68:71], v180 offset:4624
	ds_read_b64 v[104:105], v181 offset:20992
	ds_read_b128 v[88:91], v180 offset:12800
	ds_read_b128 v[92:95], v180 offset:12816
	ds_read_b128 v[72:75], v180 offset:512
	ds_read_b128 v[76:79], v180 offset:528
	ds_read_b128 v[80:83], v180 offset:8704
	ds_read_b128 v[84:87], v180 offset:8720
	ds_read_b128 v[96:99], v180 offset:16896
	ds_read_b128 v[100:103], v180 offset:16912
	s_waitcnt lgkmcnt(11)
; __device__ __forceinline__ void rwkv_block(KP p, int o, int b, int hd, LAS unsigned char* lds, const bf16_t* P, bf16_t* YB) {
;     ...
;             for (int tt = 0; tt < 16; ++tt) {
;                 const int o8 = tt * 64 + c * 8;
;                 const f32x4 ka = *(const LAS f32x4*)(KK + o8), kb = *(const LAS f32x4*)(KK + o8 + 4);
;                 const f32x4 wa = *(const LAS f32x4*)(Wd + o8), wb = *(const LAS f32x4*)(Wd + o8 + 4);
;                 const f32x4 ba = *(const LAS f32x4*)(BB + o8), bb = *(const LAS f32x4*)(BB + o8 + 4);
;                 const f32x4 ma = *(const LAS f32x4*)(KM + o8), mb = *(const LAS f32x4*)(KM + o8 + 4);
;                 const f32x4 ra = *(const LAS f32x4*)(Rr + o8), rb = *(const LAS f32x4*)(Rr + o8 + 4);
;                 const f32x2 v01 = *(const LAS f32x2*)(Vv + tt * 64 + 2 * rp);
;                 const f32x2 k2[4] = {{ka[0], ka[1]}, {ka[2], ka[3]}, {kb[0], kb[1]}, {kb[2], kb[3]}};
;                 const f32x2 w2[4] = {{wa[0], wa[1]}, {wa[2], wa[3]}, {wb[0], wb[1]}, {wb[2], wb[3]}};
;                 const f32x2 b2[4] = {{ba[0], ba[1]}, {ba[2], ba[3]}, {bb[0], bb[1]}, {bb[2], bb[3]}};
;                 const f32x2 m2[4] = {{ma[0], ma[1]}, {ma[2], ma[3]}, {mb[0], mb[1]}, {mb[2], mb[3]}};
;                 const f32x2 r2[4] = {{ra[0], ra[1]}, {ra[2], ra[3]}, {rb[0], rb[1]}, {rb[2], rb[3]}};
;                 f32x2 accA = s[0][0] * k2[0], accB = s[1][0] * k2[0], accA2 = s[0][2] * k2[2], accB2 = s[1][2] * k2[2];
;                 accA = s[0][1] * k2[1] + accA; accB = s[1][1] * k2[1] + accB; accA2 = s[0][3] * k2[3] + accA2; accB2 = s[1][3] * k2[3] + accB2;
;                 accA = accA + accA2; accB = accB + accB2;
;                 float sa0 = accA.x + accA.y, sa1 = accB.x + accB.y;
;                 sa0 += dpp_f<0xB1>(sa0); sa1 += dpp_f<0xB1>(sa1);
;                 sa0 += dpp_f<0x4E>(sa0); sa1 += dpp_f<0x4E>(sa1);
;                 sa0 += dpp_f<0x141>(sa0); sa1 += dpp_f<0x141>(sa1);
;                 const f32x2 saA = {sa0, sa0}, saB = {sa1, sa1}, vA = {v01.x, v01.x}, vB = {v01.y, v01.y};
;                 f32x2 yA, yB;
; #pragma unroll
;                 for (int j = 0; j < 4; ++j) {
;                     f32x2 tA = vA * m2[j], tB = vB * m2[j];
;                     tA = saA * b2[j] + tA; tB = saB * b2[j] + tB;
;                     s[0][j] = s[0][j] * w2[j] + tA; s[1][j] = s[1][j] * w2[j] + tB;
	v_pk_mul_f32 v[20:21], v[2:3], v[110:111] op_sel_hi:[1,0]
	v_pk_mul_f32 v[22:23], v[10:11], v[114:115] op_sel_hi:[1,0]
	v_pk_fma_f32 v[20:21], v[4:5], v[110:111], v[20:21] op_sel:[0,1,0]
	v_pk_fma_f32 v[22:23], v[12:13], v[114:115], v[22:23] op_sel:[0,1,0]
	v_pk_fma_f32 v[20:21], v[6:7], v[112:113], v[20:21] op_sel_hi:[1,0,1]
	v_pk_fma_f32 v[22:23], v[14:15], v[116:117], v[22:23] op_sel_hi:[1,0,1]
	v_pk_fma_f32 v[20:21], v[8:9], v[112:113], v[20:21] op_sel:[0,1,0]
	v_pk_fma_f32 v[22:23], v[16:17], v[116:117], v[22:23] op_sel:[0,1,0]
	v_add_f32_dpp v40, v40, v40 quad_perm:[1,0,3,2] row_mask:0xf bank_mask:0xf bound_ctrl:1
	v_pk_add_f32 v[20:21], v[20:21], v[22:23]
	v_add_f32_dpp v41, v41, v41 quad_perm:[1,0,3,2] row_mask:0xf bank_mask:0xf bound_ctrl:1
	v_add_f32_dpp v40, v40, v40 quad_perm:[2,3,0,1] row_mask:0xf bank_mask:0xf bound_ctrl:1
	v_pk_mul_f32 v[24:25], v[150:151], v[134:135] op_sel_hi:[1,0]
	v_add_f32_dpp v41, v41, v41 quad_perm:[2,3,0,1] row_mask:0xf bank_mask:0xf bound_ctrl:1
	v_add_f32_dpp v40, v40, v40 row_half_mirror row_mask:0xf bank_mask:0xf bound_ctrl:1
	v_pk_fma_f32 v[24:25], v[2:3], v[118:119], v[24:25] op_sel_hi:[1,0,1]
	v_add_f32_dpp v41, v41, v41 row_half_mirror row_mask:0xf bank_mask:0xf bound_ctrl:1
	v_pk_mul_f32 v[26:27], v[150:151], v[134:135] op_sel:[0,1]
	s_mov_b64 exec, vcc
	ds_write_b64 v181, v[40:41] offset:28672
	s_mov_b64 exec, s[12:13]
	v_pk_fma_f32 v[26:27], v[4:5], v[118:119], v[26:27] op_sel:[0,1,0]
	v_pk_mul_f32 v[28:29], v[150:151], v[136:137] op_sel_hi:[1,0]
	v_pk_mul_f32 v[30:31], v[150:151], v[136:137] op_sel:[0,1]
	v_pk_fma_f32 v[28:29], v[6:7], v[120:121], v[28:29] op_sel_hi:[1,0,1]
	v_pk_fma_f32 v[30:31], v[8:9], v[120:121], v[30:31] op_sel:[0,1,0]
	v_add_f32_dpp v20, v20, v20 quad_perm:[1,0,3,2] row_mask:0xf bank_mask:0xf bound_ctrl:1
	v_add_f32_dpp v21, v21, v21 quad_perm:[1,0,3,2] row_mask:0xf bank_mask:0xf bound_ctrl:1
	v_pk_mul_f32 v[32:33], v[150:151], v[138:139] op_sel_hi:[1,0]
	v_add_f32_dpp v20, v20, v20 quad_perm:[2,3,0,1] row_mask:0xf bank_mask:0xf bound_ctrl:1
	v_add_f32_dpp v21, v21, v21 quad_perm:[2,3,0,1] row_mask:0xf bank_mask:0xf bound_ctrl:1
	v_pk_fma_f32 v[32:33], v[10:11], v[122:123], v[32:33] op_sel_hi:[1,0,1]
	v_add_f32_dpp v20, v20, v20 row_half_mirror row_mask:0xf bank_mask:0xf bound_ctrl:1
	v_add_f32_dpp v21, v21, v21 row_half_mirror row_mask:0xf bank_mask:0xf bound_ctrl:1
	v_pk_mul_f32 v[34:35], v[150:151], v[138:139] op_sel:[0,1]
	v_pk_fma_f32 v[2:3], v[20:21], v[126:127], v[24:25] op_sel_hi:[1,0,1]
	v_pk_fma_f32 v[10:11], v[20:21], v[130:131], v[32:33] op_sel_hi:[1,0,1]
	v_pk_fma_f32 v[4:5], v[20:21], v[126:127], v[26:27] op_sel:[0,1,0]
	v_pk_fma_f32 v[6:7], v[20:21], v[128:129], v[28:29] op_sel_hi:[1,0,1]
	v_pk_fma_f32 v[8:9], v[20:21], v[128:129], v[30:31] op_sel:[0,1,0]
	v_pk_fma_f32 v[34:35], v[12:13], v[122:123], v[34:35] op_sel:[0,1,0]
	v_pk_mul_f32 v[36:37], v[150:151], v[140:141] op_sel_hi:[1,0]
	v_pk_fma_f32 v[12:13], v[20:21], v[130:131], v[34:35] op_sel:[0,1,0]
	v_pk_fma_f32 v[36:37], v[14:15], v[124:125], v[36:37] op_sel_hi:[1,0,1]
	v_pk_mul_f32 v[38:39], v[150:151], v[140:141] op_sel:[0,1]
	v_pk_fma_f32 v[14:15], v[20:21], v[132:133], v[36:37] op_sel_hi:[1,0,1]
	v_pk_fma_f32 v[38:39], v[16:17], v[124:125], v[38:39] op_sel:[0,1,0]
	v_pk_mul_f32 v[42:43], v[2:3], v[142:143] op_sel_hi:[1,0]
	v_pk_fma_f32 v[16:17], v[20:21], v[132:133], v[38:39] op_sel:[0,1,0]
	v_pk_mul_f32 v[44:45], v[10:11], v[146:147] op_sel_hi:[1,0]
	v_pk_fma_f32 v[42:43], v[4:5], v[142:143], v[42:43] op_sel:[0,1,0]
	v_pk_fma_f32 v[44:45], v[12:13], v[146:147], v[44:45] op_sel:[0,1,0]
	v_pk_fma_f32 v[42:43], v[6:7], v[144:145], v[42:43] op_sel_hi:[1,0,1]
	v_pk_fma_f32 v[44:45], v[14:15], v[148:149], v[44:45] op_sel_hi:[1,0,1]
	v_pk_fma_f32 v[42:43], v[8:9], v[144:145], v[42:43] op_sel:[0,1,0]
	v_pk_fma_f32 v[44:45], v[16:17], v[148:149], v[44:45] op_sel:[0,1,0]
	v_pk_add_f32 v[42:43], v[42:43], v[44:45]
	ds_read_b128 v[110:113], v180 offset:4864
	ds_read_b128 v[114:117], v180 offset:4880
	ds_read_b64 v[150:151], v181 offset:21248
	ds_read_b128 v[134:137], v180 offset:13056
	ds_read_b128 v[138:141], v180 offset:13072
	ds_read_b128 v[118:121], v180 offset:768
	ds_read_b128 v[122:125], v180 offset:784
	ds_read_b128 v[126:129], v180 offset:8960
	ds_read_b128 v[130:133], v180 offset:8976
	ds_read_b128 v[142:145], v180 offset:17152
	ds_read_b128 v[146:149], v180 offset:17168
	s_waitcnt lgkmcnt(11)
; __device__ __forceinline__ void rwkv_block(KP p, int o, int b, int hd, LAS unsigned char* lds, const bf16_t* P, bf16_t* YB) {
;     ...
;             for (int tt = 0; tt < 16; ++tt) {
;                 const int o8 = tt * 64 + c * 8;
;                 const f32x4 ka = *(const LAS f32x4*)(KK + o8), kb = *(const LAS f32x4*)(KK + o8 + 4);
;                 const f32x4 wa = *(const LAS f32x4*)(Wd + o8), wb = *(const LAS f32x4*)(Wd + o8 + 4);
;                 const f32x4 ba = *(const LAS f32x4*)(BB + o8), bb = *(const LAS f32x4*)(BB + o8 + 4);
;                 const f32x4 ma = *(const LAS f32x4*)(KM + o8), mb = *(const LAS f32x4*)(KM + o8 + 4);
;                 const f32x4 ra = *(const LAS f32x4*)(Rr + o8), rb = *(const LAS f32x4*)(Rr + o8 + 4);
;                 const f32x2 v01 = *(const LAS f32x2*)(Vv + tt * 64 + 2 * rp);
;                 const f32x2 k2[4] = {{ka[0], ka[1]}, {ka[2], ka[3]}, {kb[0], kb[1]}, {kb[2], kb[3]}};
;                 const f32x2 w2[4] = {{wa[0], wa[1]}, {wa[2], wa[3]}, {wb[0], wb[1]}, {wb[2], wb[3]}};
;                 const f32x2 b2[4] = {{ba[0], ba[1]}, {ba[2], ba[3]}, {bb[0], bb[1]}, {bb[2], bb[3]}};
;                 const f32x2 m2[4] = {{ma[0], ma[1]}, {ma[2], ma[3]}, {mb[0], mb[1]}, {mb[2], mb[3]}};
;                 const f32x2 r2[4] = {{ra[0], ra[1]}, {ra[2], ra[3]}, {rb[0], rb[1]}, {rb[2], rb[3]}};
;                 f32x2 accA = s[0][0] * k2[0], accB = s[1][0] * k2[0], accA2 = s[0][2] * k2[2], accB2 = s[1][2] * k2[2];
;                 accA = s[0][1] * k2[1] + accA; accB = s[1][1] * k2[1] + accB; accA2 = s[0][3] * k2[3] + accA2; accB2 = s[1][3] * k2[3] + accB2;
;                 accA = accA + accA2; accB = accB + accB2;
;                 float sa0 = accA.x + accA.y, sa1 = accB.x + accB.y;
;                 sa0 += dpp_f<0xB1>(sa0); sa1 += dpp_f<0xB1>(sa1);
;                 sa0 += dpp_f<0x4E>(sa0); sa1 += dpp_f<0x4E>(sa1);
;                 sa0 += dpp_f<0x141>(sa0); sa1 += dpp_f<0x141>(sa1);
;                 const f32x2 saA = {sa0, sa0}, saB = {sa1, sa1}, vA = {v01.x, v01.x}, vB = {v01.y, v01.y};
;                 f32x2 yA, yB;
; #pragma unroll
;                 for (int j = 0; j < 4; ++j) {
;                     f32x2 tA = vA * m2[j], tB = vB * m2[j];
;                     tA = saA * b2[j] + tA; tB = saB * b2[j] + tB;
;                     s[0][j] = s[0][j] * w2[j] + tA; s[1][j] = s[1][j] * w2[j] + tB;
	v_pk_mul_f32 v[20:21], v[2:3], v[64:65] op_sel_hi:[1,0]
	v_pk_mul_f32 v[22:23], v[10:11], v[68:69] op_sel_hi:[1,0]
	v_pk_fma_f32 v[20:21], v[4:5], v[64:65], v[20:21] op_sel:[0,1,0]
	v_pk_fma_f32 v[22:23], v[12:13], v[68:69], v[22:23] op_sel:[0,1,0]
	v_pk_fma_f32 v[20:21], v[6:7], v[66:67], v[20:21] op_sel_hi:[1,0,1]
	v_pk_fma_f32 v[22:23], v[14:15], v[70:71], v[22:23] op_sel_hi:[1,0,1]
	v_pk_fma_f32 v[20:21], v[8:9], v[66:67], v[20:21] op_sel:[0,1,0]
	v_pk_fma_f32 v[22:23], v[16:17], v[70:71], v[22:23] op_sel:[0,1,0]
	v_add_f32_dpp v42, v42, v42 quad_perm:[1,0,3,2] row_mask:0xf bank_mask:0xf bound_ctrl:1
	v_pk_add_f32 v[20:21], v[20:21], v[22:23]
	v_add_f32_dpp v43, v43, v43 quad_perm:[1,0,3,2] row_mask:0xf bank_mask:0xf bound_ctrl:1
	v_add_f32_dpp v42, v42, v42 quad_perm:[2,3,0,1] row_mask:0xf bank_mask:0xf bound_ctrl:1
	v_pk_mul_f32 v[24:25], v[104:105], v[88:89] op_sel_hi:[1,0]
	v_add_f32_dpp v43, v43, v43 quad_perm:[2,3,0,1] row_mask:0xf bank_mask:0xf bound_ctrl:1
	v_add_f32_dpp v42, v42, v42 row_half_mirror row_mask:0xf bank_mask:0xf bound_ctrl:1
	v_pk_fma_f32 v[24:25], v[2:3], v[72:73], v[24:25] op_sel_hi:[1,0,1]
	v_add_f32_dpp v43, v43, v43 row_half_mirror row_mask:0xf bank_mask:0xf bound_ctrl:1
	v_pk_mul_f32 v[26:27], v[104:105], v[88:89] op_sel:[0,1]
	s_mov_b64 exec, vcc
	ds_write_b64 v181, v[42:43] offset:28928
	s_mov_b64 exec, s[12:13]
	v_pk_fma_f32 v[26:27], v[4:5], v[72:73], v[26:27] op_sel:[0,1,0]
	v_pk_mul_f32 v[28:29], v[104:105], v[90:91] op_sel_hi:[1,0]
	v_pk_mul_f32 v[30:31], v[104:105], v[90:91] op_sel:[0,1]
	v_pk_fma_f32 v[28:29], v[6:7], v[74:75], v[28:29] op_sel_hi:[1,0,1]
	v_pk_fma_f32 v[30:31], v[8:9], v[74:75], v[30:31] op_sel:[0,1,0]
	v_add_f32_dpp v20, v20, v20 quad_perm:[1,0,3,2] row_mask:0xf bank_mask:0xf bound_ctrl:1
	v_add_f32_dpp v21, v21, v21 quad_perm:[1,0,3,2] row_mask:0xf bank_mask:0xf bound_ctrl:1
	v_pk_mul_f32 v[32:33], v[104:105], v[92:93] op_sel_hi:[1,0]
	v_add_f32_dpp v20, v20, v20 quad_perm:[2,3,0,1] row_mask:0xf bank_mask:0xf bound_ctrl:1
	v_add_f32_dpp v21, v21, v21 quad_perm:[2,3,0,1] row_mask:0xf bank_mask:0xf bound_ctrl:1
	v_pk_fma_f32 v[32:33], v[10:11], v[76:77], v[32:33] op_sel_hi:[1,0,1]
	v_add_f32_dpp v20, v20, v20 row_half_mirror row_mask:0xf bank_mask:0xf bound_ctrl:1
	v_add_f32_dpp v21, v21, v21 row_half_mirror row_mask:0xf bank_mask:0xf bound_ctrl:1
	v_pk_mul_f32 v[34:35], v[104:105], v[92:93] op_sel:[0,1]
	v_pk_fma_f32 v[2:3], v[20:21], v[80:81], v[24:25] op_sel_hi:[1,0,1]
	v_pk_fma_f32 v[10:11], v[20:21], v[84:85], v[32:33] op_sel_hi:[1,0,1]
	v_pk_fma_f32 v[4:5], v[20:21], v[80:81], v[26:27] op_sel:[0,1,0]
	v_pk_fma_f32 v[6:7], v[20:21], v[82:83], v[28:29] op_sel_hi:[1,0,1]
	v_pk_fma_f32 v[8:9], v[20:21], v[82:83], v[30:31] op_sel:[0,1,0]
	v_pk_fma_f32 v[34:35], v[12:13], v[76:77], v[34:35] op_sel:[0,1,0]
	v_pk_mul_f32 v[36:37], v[104:105], v[94:95] op_sel_hi:[1,0]
	v_pk_fma_f32 v[12:13], v[20:21], v[84:85], v[34:35] op_sel:[0,1,0]
	v_pk_fma_f32 v[36:37], v[14:15], v[78:79], v[36:37] op_sel_hi:[1,0,1]
	v_pk_mul_f32 v[38:39], v[104:105], v[94:95] op_sel:[0,1]
	v_pk_fma_f32 v[14:15], v[20:21], v[86:87], v[36:37] op_sel_hi:[1,0,1]
	v_pk_fma_f32 v[38:39], v[16:17], v[78:79], v[38:39] op_sel:[0,1,0]
	v_pk_mul_f32 v[40:41], v[2:3], v[96:97] op_sel_hi:[1,0]
	v_pk_fma_f32 v[16:17], v[20:21], v[86:87], v[38:39] op_sel:[0,1,0]
	v_pk_mul_f32 v[44:45], v[10:11], v[100:101] op_sel_hi:[1,0]
	v_pk_fma_f32 v[40:41], v[4:5], v[96:97], v[40:41] op_sel:[0,1,0]
	v_pk_fma_f32 v[44:45], v[12:13], v[100:101], v[44:45] op_sel:[0,1,0]
	v_pk_fma_f32 v[40:41], v[6:7], v[98:99], v[40:41] op_sel_hi:[1,0,1]
	v_pk_fma_f32 v[44:45], v[14:15], v[102:103], v[44:45] op_sel_hi:[1,0,1]
	v_pk_fma_f32 v[40:41], v[8:9], v[98:99], v[40:41] op_sel:[0,1,0]
	v_pk_fma_f32 v[44:45], v[16:17], v[102:103], v[44:45] op_sel:[0,1,0]
	v_pk_add_f32 v[40:41], v[40:41], v[44:45]
	ds_read_b128 v[64:67], v180 offset:5120
	ds_read_b128 v[68:71], v180 offset:5136
	ds_read_b64 v[104:105], v181 offset:21504
	ds_read_b128 v[88:91], v180 offset:13312
	ds_read_b128 v[92:95], v180 offset:13328
	ds_read_b128 v[72:75], v180 offset:1024
	ds_read_b128 v[76:79], v180 offset:1040
	ds_read_b128 v[80:83], v180 offset:9216
	ds_read_b128 v[84:87], v180 offset:9232
	ds_read_b128 v[96:99], v180 offset:17408
	ds_read_b128 v[100:103], v180 offset:17424
	s_waitcnt lgkmcnt(11)
; __device__ __forceinline__ void rwkv_block(KP p, int o, int b, int hd, LAS unsigned char* lds, const bf16_t* P, bf16_t* YB) {
;     ...
;             for (int tt = 0; tt < 16; ++tt) {
;                 const int o8 = tt * 64 + c * 8;
;                 const f32x4 ka = *(const LAS f32x4*)(KK + o8), kb = *(const LAS f32x4*)(KK + o8 + 4);
;                 const f32x4 wa = *(const LAS f32x4*)(Wd + o8), wb = *(const LAS f32x4*)(Wd + o8 + 4);
;                 const f32x4 ba = *(const LAS f32x4*)(BB + o8), bb = *(const LAS f32x4*)(BB + o8 + 4);
;                 const f32x4 ma = *(const LAS f32x4*)(KM + o8), mb = *(const LAS f32x4*)(KM + o8 + 4);
;                 const f32x4 ra = *(const LAS f32x4*)(Rr + o8), rb = *(const LAS f32x4*)(Rr + o8 + 4);
;                 const f32x2 v01 = *(const LAS f32x2*)(Vv + tt * 64 + 2 * rp);
;                 const f32x2 k2[4] = {{ka[0], ka[1]}, {ka[2], ka[3]}, {kb[0], kb[1]}, {kb[2], kb[3]}};
;                 const f32x2 w2[4] = {{wa[0], wa[1]}, {wa[2], wa[3]}, {wb[0], wb[1]}, {wb[2], wb[3]}};
;                 const f32x2 b2[4] = {{ba[0], ba[1]}, {ba[2], ba[3]}, {bb[0], bb[1]}, {bb[2], bb[3]}};
;                 const f32x2 m2[4] = {{ma[0], ma[1]}, {ma[2], ma[3]}, {mb[0], mb[1]}, {mb[2], mb[3]}};
;                 const f32x2 r2[4] = {{ra[0], ra[1]}, {ra[2], ra[3]}, {rb[0], rb[1]}, {rb[2], rb[3]}};
;                 f32x2 accA = s[0][0] * k2[0], accB = s[1][0] * k2[0], accA2 = s[0][2] * k2[2], accB2 = s[1][2] * k2[2];
;                 accA = s[0][1] * k2[1] + accA; accB = s[1][1] * k2[1] + accB; accA2 = s[0][3] * k2[3] + accA2; accB2 = s[1][3] * k2[3] + accB2;
;                 accA = accA + accA2; accB = accB + accB2;
;                 float sa0 = accA.x + accA.y, sa1 = accB.x + accB.y;
;                 sa0 += dpp_f<0xB1>(sa0); sa1 += dpp_f<0xB1>(sa1);
;                 sa0 += dpp_f<0x4E>(sa0); sa1 += dpp_f<0x4E>(sa1);
;                 sa0 += dpp_f<0x141>(sa0); sa1 += dpp_f<0x141>(sa1);
;                 const f32x2 saA = {sa0, sa0}, saB = {sa1, sa1}, vA = {v01.x, v01.x}, vB = {v01.y, v01.y};
;                 f32x2 yA, yB;
; #pragma unroll
;                 for (int j = 0; j < 4; ++j) {
;                     f32x2 tA = vA * m2[j], tB = vB * m2[j];
;                     tA = saA * b2[j] + tA; tB = saB * b2[j] + tB;
;                     s[0][j] = s[0][j] * w2[j] + tA; s[1][j] = s[1][j] * w2[j] + tB;
	v_pk_mul_f32 v[20:21], v[2:3], v[110:111] op_sel_hi:[1,0]
	v_pk_mul_f32 v[22:23], v[10:11], v[114:115] op_sel_hi:[1,0]
	v_pk_fma_f32 v[20:21], v[4:5], v[110:111], v[20:21] op_sel:[0,1,0]
	v_pk_fma_f32 v[22:23], v[12:13], v[114:115], v[22:23] op_sel:[0,1,0]
	v_pk_fma_f32 v[20:21], v[6:7], v[112:113], v[20:21] op_sel_hi:[1,0,1]
	v_pk_fma_f32 v[22:23], v[14:15], v[116:117], v[22:23] op_sel_hi:[1,0,1]
	v_pk_fma_f32 v[20:21], v[8:9], v[112:113], v[20:21] op_sel:[0,1,0]
	v_pk_fma_f32 v[22:23], v[16:17], v[116:117], v[22:23] op_sel:[0,1,0]
	v_add_f32_dpp v40, v40, v40 quad_perm:[1,0,3,2] row_mask:0xf bank_mask:0xf bound_ctrl:1
	v_pk_add_f32 v[20:21], v[20:21], v[22:23]
	v_add_f32_dpp v41, v41, v41 quad_perm:[1,0,3,2] row_mask:0xf bank_mask:0xf bound_ctrl:1
	v_add_f32_dpp v40, v40, v40 quad_perm:[2,3,0,1] row_mask:0xf bank_mask:0xf bound_ctrl:1
	v_pk_mul_f32 v[24:25], v[150:151], v[134:135] op_sel_hi:[1,0]
	v_add_f32_dpp v41, v41, v41 quad_perm:[2,3,0,1] row_mask:0xf bank_mask:0xf bound_ctrl:1
	v_add_f32_dpp v40, v40, v40 row_half_mirror row_mask:0xf bank_mask:0xf bound_ctrl:1
	v_pk_fma_f32 v[24:25], v[2:3], v[118:119], v[24:25] op_sel_hi:[1,0,1]
	v_add_f32_dpp v41, v41, v41 row_half_mirror row_mask:0xf bank_mask:0xf bound_ctrl:1
	v_pk_mul_f32 v[26:27], v[150:151], v[134:135] op_sel:[0,1]
	s_mov_b64 exec, vcc
	ds_write_b64 v181, v[40:41] offset:29184
	s_mov_b64 exec, s[12:13]
	v_pk_fma_f32 v[26:27], v[4:5], v[118:119], v[26:27] op_sel:[0,1,0]
	v_pk_mul_f32 v[28:29], v[150:151], v[136:137] op_sel_hi:[1,0]
	v_pk_mul_f32 v[30:31], v[150:151], v[136:137] op_sel:[0,1]
	v_pk_fma_f32 v[28:29], v[6:7], v[120:121], v[28:29] op_sel_hi:[1,0,1]
	v_pk_fma_f32 v[30:31], v[8:9], v[120:121], v[30:31] op_sel:[0,1,0]
	v_add_f32_dpp v20, v20, v20 quad_perm:[1,0,3,2] row_mask:0xf bank_mask:0xf bound_ctrl:1
	v_add_f32_dpp v21, v21, v21 quad_perm:[1,0,3,2] row_mask:0xf bank_mask:0xf bound_ctrl:1
	v_pk_mul_f32 v[32:33], v[150:151], v[138:139] op_sel_hi:[1,0]
	v_add_f32_dpp v20, v20, v20 quad_perm:[2,3,0,1] row_mask:0xf bank_mask:0xf bound_ctrl:1
	v_add_f32_dpp v21, v21, v21 quad_perm:[2,3,0,1] row_mask:0xf bank_mask:0xf bound_ctrl:1
	v_pk_fma_f32 v[32:33], v[10:11], v[122:123], v[32:33] op_sel_hi:[1,0,1]
	v_add_f32_dpp v20, v20, v20 row_half_mirror row_mask:0xf bank_mask:0xf bound_ctrl:1
	v_add_f32_dpp v21, v21, v21 row_half_mirror row_mask:0xf bank_mask:0xf bound_ctrl:1
	v_pk_mul_f32 v[34:35], v[150:151], v[138:139] op_sel:[0,1]
	v_pk_fma_f32 v[2:3], v[20:21], v[126:127], v[24:25] op_sel_hi:[1,0,1]
	v_pk_fma_f32 v[10:11], v[20:21], v[130:131], v[32:33] op_sel_hi:[1,0,1]
	v_pk_fma_f32 v[4:5], v[20:21], v[126:127], v[26:27] op_sel:[0,1,0]
	v_pk_fma_f32 v[6:7], v[20:21], v[128:129], v[28:29] op_sel_hi:[1,0,1]
	v_pk_fma_f32 v[8:9], v[20:21], v[128:129], v[30:31] op_sel:[0,1,0]
	v_pk_fma_f32 v[34:35], v[12:13], v[122:123], v[34:35] op_sel:[0,1,0]
	v_pk_mul_f32 v[36:37], v[150:151], v[140:141] op_sel_hi:[1,0]
	v_pk_fma_f32 v[12:13], v[20:21], v[130:131], v[34:35] op_sel:[0,1,0]
	v_pk_fma_f32 v[36:37], v[14:15], v[124:125], v[36:37] op_sel_hi:[1,0,1]
	v_pk_mul_f32 v[38:39], v[150:151], v[140:141] op_sel:[0,1]
	v_pk_fma_f32 v[14:15], v[20:21], v[132:133], v[36:37] op_sel_hi:[1,0,1]
	v_pk_fma_f32 v[38:39], v[16:17], v[124:125], v[38:39] op_sel:[0,1,0]
	v_pk_mul_f32 v[42:43], v[2:3], v[142:143] op_sel_hi:[1,0]
	v_pk_fma_f32 v[16:17], v[20:21], v[132:133], v[38:39] op_sel:[0,1,0]
	v_pk_mul_f32 v[44:45], v[10:11], v[146:147] op_sel_hi:[1,0]
	v_pk_fma_f32 v[42:43], v[4:5], v[142:143], v[42:43] op_sel:[0,1,0]
	v_pk_fma_f32 v[44:45], v[12:13], v[146:147], v[44:45] op_sel:[0,1,0]
	v_pk_fma_f32 v[42:43], v[6:7], v[144:145], v[42:43] op_sel_hi:[1,0,1]
	v_pk_fma_f32 v[44:45], v[14:15], v[148:149], v[44:45] op_sel_hi:[1,0,1]
	v_pk_fma_f32 v[42:43], v[8:9], v[144:145], v[42:43] op_sel:[0,1,0]
	v_pk_fma_f32 v[44:45], v[16:17], v[148:149], v[44:45] op_sel:[0,1,0]
	v_pk_add_f32 v[42:43], v[42:43], v[44:45]
	ds_read_b128 v[110:113], v180 offset:5376
	ds_read_b128 v[114:117], v180 offset:5392
	ds_read_b64 v[150:151], v181 offset:21760
	ds_read_b128 v[134:137], v180 offset:13568
	ds_read_b128 v[138:141], v180 offset:13584
	ds_read_b128 v[118:121], v180 offset:1280
	ds_read_b128 v[122:125], v180 offset:1296
	ds_read_b128 v[126:129], v180 offset:9472
	ds_read_b128 v[130:133], v180 offset:9488
	ds_read_b128 v[142:145], v180 offset:17664
	ds_read_b128 v[146:149], v180 offset:17680
	s_waitcnt lgkmcnt(11)
; __device__ __forceinline__ void rwkv_block(KP p, int o, int b, int hd, LAS unsigned char* lds, const bf16_t* P, bf16_t* YB) {
;     ...
;             for (int tt = 0; tt < 16; ++tt) {
;                 const int o8 = tt * 64 + c * 8;
;                 const f32x4 ka = *(const LAS f32x4*)(KK + o8), kb = *(const LAS f32x4*)(KK + o8 + 4);
;                 const f32x4 wa = *(const LAS f32x4*)(Wd + o8), wb = *(const LAS f32x4*)(Wd + o8 + 4);
;                 const f32x4 ba = *(const LAS f32x4*)(BB + o8), bb = *(const LAS f32x4*)(BB + o8 + 4);
;                 const f32x4 ma = *(const LAS f32x4*)(KM + o8), mb = *(const LAS f32x4*)(KM + o8 + 4);
;                 const f32x4 ra = *(const LAS f32x4*)(Rr + o8), rb = *(const LAS f32x4*)(Rr + o8 + 4);
;                 const f32x2 v01 = *(const LAS f32x2*)(Vv + tt * 64 + 2 * rp);
;                 const f32x2 k2[4] = {{ka[0], ka[1]}, {ka[2], ka[3]}, {kb[0], kb[1]}, {kb[2], kb[3]}};
;                 const f32x2 w2[4] = {{wa[0], wa[1]}, {wa[2], wa[3]}, {wb[0], wb[1]}, {wb[2], wb[3]}};
;                 const f32x2 b2[4] = {{ba[0], ba[1]}, {ba[2], ba[3]}, {bb[0], bb[1]}, {bb[2], bb[3]}};
;                 const f32x2 m2[4] = {{ma[0], ma[1]}, {ma[2], ma[3]}, {mb[0], mb[1]}, {mb[2], mb[3]}};
;                 const f32x2 r2[4] = {{ra[0], ra[1]}, {ra[2], ra[3]}, {rb[0], rb[1]}, {rb[2], rb[3]}};
;                 f32x2 accA = s[0][0] * k2[0], accB = s[1][0] * k2[0], accA2 = s[0][2] * k2[2], accB2 = s[1][2] * k2[2];
;                 accA = s[0][1] * k2[1] + accA; accB = s[1][1] * k2[1] + accB; accA2 = s[0][3] * k2[3] + accA2; accB2 = s[1][3] * k2[3] + accB2;
;                 accA = accA + accA2; accB = accB + accB2;
;                 float sa0 = accA.x + accA.y, sa1 = accB.x + accB.y;
;                 sa0 += dpp_f<0xB1>(sa0); sa1 += dpp_f<0xB1>(sa1);
;                 sa0 += dpp_f<0x4E>(sa0); sa1 += dpp_f<0x4E>(sa1);
;                 sa0 += dpp_f<0x141>(sa0); sa1 += dpp_f<0x141>(sa1);
;                 const f32x2 saA = {sa0, sa0}, saB = {sa1, sa1}, vA = {v01.x, v01.x}, vB = {v01.y, v01.y};
;                 f32x2 yA, yB;
; #pragma unroll
;                 for (int j = 0; j < 4; ++j) {
;                     f32x2 tA = vA * m2[j], tB = vB * m2[j];
;                     tA = saA * b2[j] + tA; tB = saB * b2[j] + tB;
;                     s[0][j] = s[0][j] * w2[j] + tA; s[1][j] = s[1][j] * w2[j] + tB;
	v_pk_mul_f32 v[20:21], v[2:3], v[64:65] op_sel_hi:[1,0]
	v_pk_mul_f32 v[22:23], v[10:11], v[68:69] op_sel_hi:[1,0]
	v_pk_fma_f32 v[20:21], v[4:5], v[64:65], v[20:21] op_sel:[0,1,0]
	v_pk_fma_f32 v[22:23], v[12:13], v[68:69], v[22:23] op_sel:[0,1,0]
	v_pk_fma_f32 v[20:21], v[6:7], v[66:67], v[20:21] op_sel_hi:[1,0,1]
	v_pk_fma_f32 v[22:23], v[14:15], v[70:71], v[22:23] op_sel_hi:[1,0,1]
	v_pk_fma_f32 v[20:21], v[8:9], v[66:67], v[20:21] op_sel:[0,1,0]
	v_pk_fma_f32 v[22:23], v[16:17], v[70:71], v[22:23] op_sel:[0,1,0]
	v_add_f32_dpp v42, v42, v42 quad_perm:[1,0,3,2] row_mask:0xf bank_mask:0xf bound_ctrl:1
	v_pk_add_f32 v[20:21], v[20:21], v[22:23]
	v_add_f32_dpp v43, v43, v43 quad_perm:[1,0,3,2] row_mask:0xf bank_mask:0xf bound_ctrl:1
	v_add_f32_dpp v42, v42, v42 quad_perm:[2,3,0,1] row_mask:0xf bank_mask:0xf bound_ctrl:1
	v_pk_mul_f32 v[24:25], v[104:105], v[88:89] op_sel_hi:[1,0]
	v_add_f32_dpp v43, v43, v43 quad_perm:[2,3,0,1] row_mask:0xf bank_mask:0xf bound_ctrl:1
	v_add_f32_dpp v42, v42, v42 row_half_mirror row_mask:0xf bank_mask:0xf bound_ctrl:1
	v_pk_fma_f32 v[24:25], v[2:3], v[72:73], v[24:25] op_sel_hi:[1,0,1]
	v_add_f32_dpp v43, v43, v43 row_half_mirror row_mask:0xf bank_mask:0xf bound_ctrl:1
	v_pk_mul_f32 v[26:27], v[104:105], v[88:89] op_sel:[0,1]
	s_mov_b64 exec, vcc
	ds_write_b64 v181, v[42:43] offset:29440
	s_mov_b64 exec, s[12:13]
	v_pk_fma_f32 v[26:27], v[4:5], v[72:73], v[26:27] op_sel:[0,1,0]
	v_pk_mul_f32 v[28:29], v[104:105], v[90:91] op_sel_hi:[1,0]
	v_pk_mul_f32 v[30:31], v[104:105], v[90:91] op_sel:[0,1]
	v_pk_fma_f32 v[28:29], v[6:7], v[74:75], v[28:29] op_sel_hi:[1,0,1]
	v_pk_fma_f32 v[30:31], v[8:9], v[74:75], v[30:31] op_sel:[0,1,0]
	v_add_f32_dpp v20, v20, v20 quad_perm:[1,0,3,2] row_mask:0xf bank_mask:0xf bound_ctrl:1
	v_add_f32_dpp v21, v21, v21 quad_perm:[1,0,3,2] row_mask:0xf bank_mask:0xf bound_ctrl:1
	v_pk_mul_f32 v[32:33], v[104:105], v[92:93] op_sel_hi:[1,0]
	v_add_f32_dpp v20, v20, v20 quad_perm:[2,3,0,1] row_mask:0xf bank_mask:0xf bound_ctrl:1
	v_add_f32_dpp v21, v21, v21 quad_perm:[2,3,0,1] row_mask:0xf bank_mask:0xf bound_ctrl:1
	v_pk_fma_f32 v[32:33], v[10:11], v[76:77], v[32:33] op_sel_hi:[1,0,1]
	v_add_f32_dpp v20, v20, v20 row_half_mirror row_mask:0xf bank_mask:0xf bound_ctrl:1
	v_add_f32_dpp v21, v21, v21 row_half_mirror row_mask:0xf bank_mask:0xf bound_ctrl:1
	v_pk_mul_f32 v[34:35], v[104:105], v[92:93] op_sel:[0,1]
	v_pk_fma_f32 v[2:3], v[20:21], v[80:81], v[24:25] op_sel_hi:[1,0,1]
	v_pk_fma_f32 v[10:11], v[20:21], v[84:85], v[32:33] op_sel_hi:[1,0,1]
	v_pk_fma_f32 v[4:5], v[20:21], v[80:81], v[26:27] op_sel:[0,1,0]
	v_pk_fma_f32 v[6:7], v[20:21], v[82:83], v[28:29] op_sel_hi:[1,0,1]
	v_pk_fma_f32 v[8:9], v[20:21], v[82:83], v[30:31] op_sel:[0,1,0]
	v_pk_fma_f32 v[34:35], v[12:13], v[76:77], v[34:35] op_sel:[0,1,0]
	v_pk_mul_f32 v[36:37], v[104:105], v[94:95] op_sel_hi:[1,0]
	v_pk_fma_f32 v[12:13], v[20:21], v[84:85], v[34:35] op_sel:[0,1,0]
	v_pk_fma_f32 v[36:37], v[14:15], v[78:79], v[36:37] op_sel_hi:[1,0,1]
	v_pk_mul_f32 v[38:39], v[104:105], v[94:95] op_sel:[0,1]
	v_pk_fma_f32 v[14:15], v[20:21], v[86:87], v[36:37] op_sel_hi:[1,0,1]
	v_pk_fma_f32 v[38:39], v[16:17], v[78:79], v[38:39] op_sel:[0,1,0]
	v_pk_mul_f32 v[40:41], v[2:3], v[96:97] op_sel_hi:[1,0]
	v_pk_fma_f32 v[16:17], v[20:21], v[86:87], v[38:39] op_sel:[0,1,0]
	v_pk_mul_f32 v[44:45], v[10:11], v[100:101] op_sel_hi:[1,0]
	v_pk_fma_f32 v[40:41], v[4:5], v[96:97], v[40:41] op_sel:[0,1,0]
	v_pk_fma_f32 v[44:45], v[12:13], v[100:101], v[44:45] op_sel:[0,1,0]
	v_pk_fma_f32 v[40:41], v[6:7], v[98:99], v[40:41] op_sel_hi:[1,0,1]
	v_pk_fma_f32 v[44:45], v[14:15], v[102:103], v[44:45] op_sel_hi:[1,0,1]
	v_pk_fma_f32 v[40:41], v[8:9], v[98:99], v[40:41] op_sel:[0,1,0]
	v_pk_fma_f32 v[44:45], v[16:17], v[102:103], v[44:45] op_sel:[0,1,0]
	v_pk_add_f32 v[40:41], v[40:41], v[44:45]
	ds_read_b128 v[64:67], v180 offset:5632
	ds_read_b128 v[68:71], v180 offset:5648
	ds_read_b64 v[104:105], v181 offset:22016
	ds_read_b128 v[88:91], v180 offset:13824
	ds_read_b128 v[92:95], v180 offset:13840
	ds_read_b128 v[72:75], v180 offset:1536
	ds_read_b128 v[76:79], v180 offset:1552
	ds_read_b128 v[80:83], v180 offset:9728
	ds_read_b128 v[84:87], v180 offset:9744
	ds_read_b128 v[96:99], v180 offset:17920
	ds_read_b128 v[100:103], v180 offset:17936
	s_waitcnt lgkmcnt(11)
; __device__ __forceinline__ void rwkv_block(KP p, int o, int b, int hd, LAS unsigned char* lds, const bf16_t* P, bf16_t* YB) {
;     ...
;             for (int tt = 0; tt < 16; ++tt) {
;                 const int o8 = tt * 64 + c * 8;
;                 const f32x4 ka = *(const LAS f32x4*)(KK + o8), kb = *(const LAS f32x4*)(KK + o8 + 4);
;                 const f32x4 wa = *(const LAS f32x4*)(Wd + o8), wb = *(const LAS f32x4*)(Wd + o8 + 4);
;                 const f32x4 ba = *(const LAS f32x4*)(BB + o8), bb = *(const LAS f32x4*)(BB + o8 + 4);
;                 const f32x4 ma = *(const LAS f32x4*)(KM + o8), mb = *(const LAS f32x4*)(KM + o8 + 4);
;                 const f32x4 ra = *(const LAS f32x4*)(Rr + o8), rb = *(const LAS f32x4*)(Rr + o8 + 4);
;                 const f32x2 v01 = *(const LAS f32x2*)(Vv + tt * 64 + 2 * rp);
;                 const f32x2 k2[4] = {{ka[0], ka[1]}, {ka[2], ka[3]}, {kb[0], kb[1]}, {kb[2], kb[3]}};
;                 const f32x2 w2[4] = {{wa[0], wa[1]}, {wa[2], wa[3]}, {wb[0], wb[1]}, {wb[2], wb[3]}};
;                 const f32x2 b2[4] = {{ba[0], ba[1]}, {ba[2], ba[3]}, {bb[0], bb[1]}, {bb[2], bb[3]}};
;                 const f32x2 m2[4] = {{ma[0], ma[1]}, {ma[2], ma[3]}, {mb[0], mb[1]}, {mb[2], mb[3]}};
;                 const f32x2 r2[4] = {{ra[0], ra[1]}, {ra[2], ra[3]}, {rb[0], rb[1]}, {rb[2], rb[3]}};
;                 f32x2 accA = s[0][0] * k2[0], accB = s[1][0] * k2[0], accA2 = s[0][2] * k2[2], accB2 = s[1][2] * k2[2];
;                 accA = s[0][1] * k2[1] + accA; accB = s[1][1] * k2[1] + accB; accA2 = s[0][3] * k2[3] + accA2; accB2 = s[1][3] * k2[3] + accB2;
;                 accA = accA + accA2; accB = accB + accB2;
;                 float sa0 = accA.x + accA.y, sa1 = accB.x + accB.y;
;                 sa0 += dpp_f<0xB1>(sa0); sa1 += dpp_f<0xB1>(sa1);
;                 sa0 += dpp_f<0x4E>(sa0); sa1 += dpp_f<0x4E>(sa1);
;                 sa0 += dpp_f<0x141>(sa0); sa1 += dpp_f<0x141>(sa1);
;                 const f32x2 saA = {sa0, sa0}, saB = {sa1, sa1}, vA = {v01.x, v01.x}, vB = {v01.y, v01.y};
;                 f32x2 yA, yB;
; #pragma unroll
;                 for (int j = 0; j < 4; ++j) {
;                     f32x2 tA = vA * m2[j], tB = vB * m2[j];
;                     tA = saA * b2[j] + tA; tB = saB * b2[j] + tB;
;                     s[0][j] = s[0][j] * w2[j] + tA; s[1][j] = s[1][j] * w2[j] + tB;
	v_pk_mul_f32 v[20:21], v[2:3], v[110:111] op_sel_hi:[1,0]
	v_pk_mul_f32 v[22:23], v[10:11], v[114:115] op_sel_hi:[1,0]
	v_pk_fma_f32 v[20:21], v[4:5], v[110:111], v[20:21] op_sel:[0,1,0]
	v_pk_fma_f32 v[22:23], v[12:13], v[114:115], v[22:23] op_sel:[0,1,0]
	v_pk_fma_f32 v[20:21], v[6:7], v[112:113], v[20:21] op_sel_hi:[1,0,1]
	v_pk_fma_f32 v[22:23], v[14:15], v[116:117], v[22:23] op_sel_hi:[1,0,1]
	v_pk_fma_f32 v[20:21], v[8:9], v[112:113], v[20:21] op_sel:[0,1,0]
	v_pk_fma_f32 v[22:23], v[16:17], v[116:117], v[22:23] op_sel:[0,1,0]
	v_add_f32_dpp v40, v40, v40 quad_perm:[1,0,3,2] row_mask:0xf bank_mask:0xf bound_ctrl:1
	v_pk_add_f32 v[20:21], v[20:21], v[22:23]
	v_add_f32_dpp v41, v41, v41 quad_perm:[1,0,3,2] row_mask:0xf bank_mask:0xf bound_ctrl:1
	v_add_f32_dpp v40, v40, v40 quad_perm:[2,3,0,1] row_mask:0xf bank_mask:0xf bound_ctrl:1
	v_pk_mul_f32 v[24:25], v[150:151], v[134:135] op_sel_hi:[1,0]
	v_add_f32_dpp v41, v41, v41 quad_perm:[2,3,0,1] row_mask:0xf bank_mask:0xf bound_ctrl:1
	v_add_f32_dpp v40, v40, v40 row_half_mirror row_mask:0xf bank_mask:0xf bound_ctrl:1
	v_pk_fma_f32 v[24:25], v[2:3], v[118:119], v[24:25] op_sel_hi:[1,0,1]
	v_add_f32_dpp v41, v41, v41 row_half_mirror row_mask:0xf bank_mask:0xf bound_ctrl:1
	v_pk_mul_f32 v[26:27], v[150:151], v[134:135] op_sel:[0,1]
	s_mov_b64 exec, vcc
	ds_write_b64 v181, v[40:41] offset:29696
	s_mov_b64 exec, s[12:13]
	v_pk_fma_f32 v[26:27], v[4:5], v[118:119], v[26:27] op_sel:[0,1,0]
	v_pk_mul_f32 v[28:29], v[150:151], v[136:137] op_sel_hi:[1,0]
	v_pk_mul_f32 v[30:31], v[150:151], v[136:137] op_sel:[0,1]
	v_pk_fma_f32 v[28:29], v[6:7], v[120:121], v[28:29] op_sel_hi:[1,0,1]
	v_pk_fma_f32 v[30:31], v[8:9], v[120:121], v[30:31] op_sel:[0,1,0]
	v_add_f32_dpp v20, v20, v20 quad_perm:[1,0,3,2] row_mask:0xf bank_mask:0xf bound_ctrl:1
	v_add_f32_dpp v21, v21, v21 quad_perm:[1,0,3,2] row_mask:0xf bank_mask:0xf bound_ctrl:1
	v_pk_mul_f32 v[32:33], v[150:151], v[138:139] op_sel_hi:[1,0]
	v_add_f32_dpp v20, v20, v20 quad_perm:[2,3,0,1] row_mask:0xf bank_mask:0xf bound_ctrl:1
	v_add_f32_dpp v21, v21, v21 quad_perm:[2,3,0,1] row_mask:0xf bank_mask:0xf bound_ctrl:1
	v_pk_fma_f32 v[32:33], v[10:11], v[122:123], v[32:33] op_sel_hi:[1,0,1]
	v_add_f32_dpp v20, v20, v20 row_half_mirror row_mask:0xf bank_mask:0xf bound_ctrl:1
	v_add_f32_dpp v21, v21, v21 row_half_mirror row_mask:0xf bank_mask:0xf bound_ctrl:1
	v_pk_mul_f32 v[34:35], v[150:151], v[138:139] op_sel:[0,1]
	v_pk_fma_f32 v[2:3], v[20:21], v[126:127], v[24:25] op_sel_hi:[1,0,1]
	v_pk_fma_f32 v[10:11], v[20:21], v[130:131], v[32:33] op_sel_hi:[1,0,1]
	v_pk_fma_f32 v[4:5], v[20:21], v[126:127], v[26:27] op_sel:[0,1,0]
	v_pk_fma_f32 v[6:7], v[20:21], v[128:129], v[28:29] op_sel_hi:[1,0,1]
	v_pk_fma_f32 v[8:9], v[20:21], v[128:129], v[30:31] op_sel:[0,1,0]
	v_pk_fma_f32 v[34:35], v[12:13], v[122:123], v[34:35] op_sel:[0,1,0]
	v_pk_mul_f32 v[36:37], v[150:151], v[140:141] op_sel_hi:[1,0]
	v_pk_fma_f32 v[12:13], v[20:21], v[130:131], v[34:35] op_sel:[0,1,0]
	v_pk_fma_f32 v[36:37], v[14:15], v[124:125], v[36:37] op_sel_hi:[1,0,1]
	v_pk_mul_f32 v[38:39], v[150:151], v[140:141] op_sel:[0,1]
	v_pk_fma_f32 v[14:15], v[20:21], v[132:133], v[36:37] op_sel_hi:[1,0,1]
	v_pk_fma_f32 v[38:39], v[16:17], v[124:125], v[38:39] op_sel:[0,1,0]
	v_pk_mul_f32 v[42:43], v[2:3], v[142:143] op_sel_hi:[1,0]
	v_pk_fma_f32 v[16:17], v[20:21], v[132:133], v[38:39] op_sel:[0,1,0]
	v_pk_mul_f32 v[44:45], v[10:11], v[146:147] op_sel_hi:[1,0]
	v_pk_fma_f32 v[42:43], v[4:5], v[142:143], v[42:43] op_sel:[0,1,0]
	v_pk_fma_f32 v[44:45], v[12:13], v[146:147], v[44:45] op_sel:[0,1,0]
	v_pk_fma_f32 v[42:43], v[6:7], v[144:145], v[42:43] op_sel_hi:[1,0,1]
	v_pk_fma_f32 v[44:45], v[14:15], v[148:149], v[44:45] op_sel_hi:[1,0,1]
	v_pk_fma_f32 v[42:43], v[8:9], v[144:145], v[42:43] op_sel:[0,1,0]
	v_pk_fma_f32 v[44:45], v[16:17], v[148:149], v[44:45] op_sel:[0,1,0]
	v_pk_add_f32 v[42:43], v[42:43], v[44:45]
	ds_read_b128 v[110:113], v180 offset:5888
	ds_read_b128 v[114:117], v180 offset:5904
	ds_read_b64 v[150:151], v181 offset:22272
	ds_read_b128 v[134:137], v180 offset:14080
	ds_read_b128 v[138:141], v180 offset:14096
	ds_read_b128 v[118:121], v180 offset:1792
	ds_read_b128 v[122:125], v180 offset:1808
	ds_read_b128 v[126:129], v180 offset:9984
	ds_read_b128 v[130:133], v180 offset:10000
	ds_read_b128 v[142:145], v180 offset:18176
	ds_read_b128 v[146:149], v180 offset:18192
	s_waitcnt lgkmcnt(11)
; __device__ __forceinline__ void rwkv_block(KP p, int o, int b, int hd, LAS unsigned char* lds, const bf16_t* P, bf16_t* YB) {
;     ...
;             for (int tt = 0; tt < 16; ++tt) {
;                 const int o8 = tt * 64 + c * 8;
;                 const f32x4 ka = *(const LAS f32x4*)(KK + o8), kb = *(const LAS f32x4*)(KK + o8 + 4);
;                 const f32x4 wa = *(const LAS f32x4*)(Wd + o8), wb = *(const LAS f32x4*)(Wd + o8 + 4);
;                 const f32x4 ba = *(const LAS f32x4*)(BB + o8), bb = *(const LAS f32x4*)(BB + o8 + 4);
;                 const f32x4 ma = *(const LAS f32x4*)(KM + o8), mb = *(const LAS f32x4*)(KM + o8 + 4);
;                 const f32x4 ra = *(const LAS f32x4*)(Rr + o8), rb = *(const LAS f32x4*)(Rr + o8 + 4);
;                 const f32x2 v01 = *(const LAS f32x2*)(Vv + tt * 64 + 2 * rp);
;                 const f32x2 k2[4] = {{ka[0], ka[1]}, {ka[2], ka[3]}, {kb[0], kb[1]}, {kb[2], kb[3]}};
;                 const f32x2 w2[4] = {{wa[0], wa[1]}, {wa[2], wa[3]}, {wb[0], wb[1]}, {wb[2], wb[3]}};
;                 const f32x2 b2[4] = {{ba[0], ba[1]}, {ba[2], ba[3]}, {bb[0], bb[1]}, {bb[2], bb[3]}};
;                 const f32x2 m2[4] = {{ma[0], ma[1]}, {ma[2], ma[3]}, {mb[0], mb[1]}, {mb[2], mb[3]}};
;                 const f32x2 r2[4] = {{ra[0], ra[1]}, {ra[2], ra[3]}, {rb[0], rb[1]}, {rb[2], rb[3]}};
;                 f32x2 accA = s[0][0] * k2[0], accB = s[1][0] * k2[0], accA2 = s[0][2] * k2[2], accB2 = s[1][2] * k2[2];
;                 accA = s[0][1] * k2[1] + accA; accB = s[1][1] * k2[1] + accB; accA2 = s[0][3] * k2[3] + accA2; accB2 = s[1][3] * k2[3] + accB2;
;                 accA = accA + accA2; accB = accB + accB2;
;                 float sa0 = accA.x + accA.y, sa1 = accB.x + accB.y;
;                 sa0 += dpp_f<0xB1>(sa0); sa1 += dpp_f<0xB1>(sa1);
;                 sa0 += dpp_f<0x4E>(sa0); sa1 += dpp_f<0x4E>(sa1);
;                 sa0 += dpp_f<0x141>(sa0); sa1 += dpp_f<0x141>(sa1);
;                 const f32x2 saA = {sa0, sa0}, saB = {sa1, sa1}, vA = {v01.x, v01.x}, vB = {v01.y, v01.y};
;                 f32x2 yA, yB;
; #pragma unroll
;                 for (int j = 0; j < 4; ++j) {
;                     f32x2 tA = vA * m2[j], tB = vB * m2[j];
;                     tA = saA * b2[j] + tA; tB = saB * b2[j] + tB;
;                     s[0][j] = s[0][j] * w2[j] + tA; s[1][j] = s[1][j] * w2[j] + tB;
	v_pk_mul_f32 v[20:21], v[2:3], v[64:65] op_sel_hi:[1,0]
	v_pk_mul_f32 v[22:23], v[10:11], v[68:69] op_sel_hi:[1,0]
	v_pk_fma_f32 v[20:21], v[4:5], v[64:65], v[20:21] op_sel:[0,1,0]
	v_pk_fma_f32 v[22:23], v[12:13], v[68:69], v[22:23] op_sel:[0,1,0]
	v_pk_fma_f32 v[20:21], v[6:7], v[66:67], v[20:21] op_sel_hi:[1,0,1]
	v_pk_fma_f32 v[22:23], v[14:15], v[70:71], v[22:23] op_sel_hi:[1,0,1]
	v_pk_fma_f32 v[20:21], v[8:9], v[66:67], v[20:21] op_sel:[0,1,0]
	v_pk_fma_f32 v[22:23], v[16:17], v[70:71], v[22:23] op_sel:[0,1,0]
	v_add_f32_dpp v42, v42, v42 quad_perm:[1,0,3,2] row_mask:0xf bank_mask:0xf bound_ctrl:1
	v_pk_add_f32 v[20:21], v[20:21], v[22:23]
	v_add_f32_dpp v43, v43, v43 quad_perm:[1,0,3,2] row_mask:0xf bank_mask:0xf bound_ctrl:1
	v_add_f32_dpp v42, v42, v42 quad_perm:[2,3,0,1] row_mask:0xf bank_mask:0xf bound_ctrl:1
	v_pk_mul_f32 v[24:25], v[104:105], v[88:89] op_sel_hi:[1,0]
	v_add_f32_dpp v43, v43, v43 quad_perm:[2,3,0,1] row_mask:0xf bank_mask:0xf bound_ctrl:1
	v_add_f32_dpp v42, v42, v42 row_half_mirror row_mask:0xf bank_mask:0xf bound_ctrl:1
	v_pk_fma_f32 v[24:25], v[2:3], v[72:73], v[24:25] op_sel_hi:[1,0,1]
	v_add_f32_dpp v43, v43, v43 row_half_mirror row_mask:0xf bank_mask:0xf bound_ctrl:1
	v_pk_mul_f32 v[26:27], v[104:105], v[88:89] op_sel:[0,1]
	s_mov_b64 exec, vcc
	ds_write_b64 v181, v[42:43] offset:29952
	s_mov_b64 exec, s[12:13]
	v_pk_fma_f32 v[26:27], v[4:5], v[72:73], v[26:27] op_sel:[0,1,0]
	v_pk_mul_f32 v[28:29], v[104:105], v[90:91] op_sel_hi:[1,0]
	v_pk_mul_f32 v[30:31], v[104:105], v[90:91] op_sel:[0,1]
	v_pk_fma_f32 v[28:29], v[6:7], v[74:75], v[28:29] op_sel_hi:[1,0,1]
	v_pk_fma_f32 v[30:31], v[8:9], v[74:75], v[30:31] op_sel:[0,1,0]
	v_add_f32_dpp v20, v20, v20 quad_perm:[1,0,3,2] row_mask:0xf bank_mask:0xf bound_ctrl:1
	v_add_f32_dpp v21, v21, v21 quad_perm:[1,0,3,2] row_mask:0xf bank_mask:0xf bound_ctrl:1
	v_pk_mul_f32 v[32:33], v[104:105], v[92:93] op_sel_hi:[1,0]
	v_add_f32_dpp v20, v20, v20 quad_perm:[2,3,0,1] row_mask:0xf bank_mask:0xf bound_ctrl:1
	v_add_f32_dpp v21, v21, v21 quad_perm:[2,3,0,1] row_mask:0xf bank_mask:0xf bound_ctrl:1
	v_pk_fma_f32 v[32:33], v[10:11], v[76:77], v[32:33] op_sel_hi:[1,0,1]
	v_add_f32_dpp v20, v20, v20 row_half_mirror row_mask:0xf bank_mask:0xf bound_ctrl:1
	v_add_f32_dpp v21, v21, v21 row_half_mirror row_mask:0xf bank_mask:0xf bound_ctrl:1
	v_pk_mul_f32 v[34:35], v[104:105], v[92:93] op_sel:[0,1]
	v_pk_fma_f32 v[2:3], v[20:21], v[80:81], v[24:25] op_sel_hi:[1,0,1]
	v_pk_fma_f32 v[10:11], v[20:21], v[84:85], v[32:33] op_sel_hi:[1,0,1]
	v_pk_fma_f32 v[4:5], v[20:21], v[80:81], v[26:27] op_sel:[0,1,0]
	v_pk_fma_f32 v[6:7], v[20:21], v[82:83], v[28:29] op_sel_hi:[1,0,1]
	v_pk_fma_f32 v[8:9], v[20:21], v[82:83], v[30:31] op_sel:[0,1,0]
	v_pk_fma_f32 v[34:35], v[12:13], v[76:77], v[34:35] op_sel:[0,1,0]
	v_pk_mul_f32 v[36:37], v[104:105], v[94:95] op_sel_hi:[1,0]
	v_pk_fma_f32 v[12:13], v[20:21], v[84:85], v[34:35] op_sel:[0,1,0]
	v_pk_fma_f32 v[36:37], v[14:15], v[78:79], v[36:37] op_sel_hi:[1,0,1]
	v_pk_mul_f32 v[38:39], v[104:105], v[94:95] op_sel:[0,1]
	v_pk_fma_f32 v[14:15], v[20:21], v[86:87], v[36:37] op_sel_hi:[1,0,1]
	v_pk_fma_f32 v[38:39], v[16:17], v[78:79], v[38:39] op_sel:[0,1,0]
	v_pk_mul_f32 v[40:41], v[2:3], v[96:97] op_sel_hi:[1,0]
	v_pk_fma_f32 v[16:17], v[20:21], v[86:87], v[38:39] op_sel:[0,1,0]
	v_pk_mul_f32 v[44:45], v[10:11], v[100:101] op_sel_hi:[1,0]
	v_pk_fma_f32 v[40:41], v[4:5], v[96:97], v[40:41] op_sel:[0,1,0]
	v_pk_fma_f32 v[44:45], v[12:13], v[100:101], v[44:45] op_sel:[0,1,0]
	v_pk_fma_f32 v[40:41], v[6:7], v[98:99], v[40:41] op_sel_hi:[1,0,1]
	v_pk_fma_f32 v[44:45], v[14:15], v[102:103], v[44:45] op_sel_hi:[1,0,1]
	v_pk_fma_f32 v[40:41], v[8:9], v[98:99], v[40:41] op_sel:[0,1,0]
	v_pk_fma_f32 v[44:45], v[16:17], v[102:103], v[44:45] op_sel:[0,1,0]
	v_pk_add_f32 v[40:41], v[40:41], v[44:45]
	ds_read_b128 v[64:67], v180 offset:6144
	ds_read_b128 v[68:71], v180 offset:6160
	ds_read_b64 v[104:105], v181 offset:22528
	ds_read_b128 v[88:91], v180 offset:14336
	ds_read_b128 v[92:95], v180 offset:14352
	ds_read_b128 v[72:75], v180 offset:2048
	ds_read_b128 v[76:79], v180 offset:2064
	ds_read_b128 v[80:83], v180 offset:10240
	ds_read_b128 v[84:87], v180 offset:10256
	ds_read_b128 v[96:99], v180 offset:18432
	ds_read_b128 v[100:103], v180 offset:18448
	s_waitcnt lgkmcnt(11)
; __device__ __forceinline__ void rwkv_block(KP p, int o, int b, int hd, LAS unsigned char* lds, const bf16_t* P, bf16_t* YB) {
;     ...
;             for (int tt = 0; tt < 16; ++tt) {
;                 const int o8 = tt * 64 + c * 8;
;                 const f32x4 ka = *(const LAS f32x4*)(KK + o8), kb = *(const LAS f32x4*)(KK + o8 + 4);
;                 const f32x4 wa = *(const LAS f32x4*)(Wd + o8), wb = *(const LAS f32x4*)(Wd + o8 + 4);
;                 const f32x4 ba = *(const LAS f32x4*)(BB + o8), bb = *(const LAS f32x4*)(BB + o8 + 4);
;                 const f32x4 ma = *(const LAS f32x4*)(KM + o8), mb = *(const LAS f32x4*)(KM + o8 + 4);
;                 const f32x4 ra = *(const LAS f32x4*)(Rr + o8), rb = *(const LAS f32x4*)(Rr + o8 + 4);
;                 const f32x2 v01 = *(const LAS f32x2*)(Vv + tt * 64 + 2 * rp);
;                 const f32x2 k2[4] = {{ka[0], ka[1]}, {ka[2], ka[3]}, {kb[0], kb[1]}, {kb[2], kb[3]}};
;                 const f32x2 w2[4] = {{wa[0], wa[1]}, {wa[2], wa[3]}, {wb[0], wb[1]}, {wb[2], wb[3]}};
;                 const f32x2 b2[4] = {{ba[0], ba[1]}, {ba[2], ba[3]}, {bb[0], bb[1]}, {bb[2], bb[3]}};
;                 const f32x2 m2[4] = {{ma[0], ma[1]}, {ma[2], ma[3]}, {mb[0], mb[1]}, {mb[2], mb[3]}};
;                 const f32x2 r2[4] = {{ra[0], ra[1]}, {ra[2], ra[3]}, {rb[0], rb[1]}, {rb[2], rb[3]}};
;                 f32x2 accA = s[0][0] * k2[0], accB = s[1][0] * k2[0], accA2 = s[0][2] * k2[2], accB2 = s[1][2] * k2[2];
;                 accA = s[0][1] * k2[1] + accA; accB = s[1][1] * k2[1] + accB; accA2 = s[0][3] * k2[3] + accA2; accB2 = s[1][3] * k2[3] + accB2;
;                 accA = accA + accA2; accB = accB + accB2;
;                 float sa0 = accA.x + accA.y, sa1 = accB.x + accB.y;
;                 sa0 += dpp_f<0xB1>(sa0); sa1 += dpp_f<0xB1>(sa1);
;                 sa0 += dpp_f<0x4E>(sa0); sa1 += dpp_f<0x4E>(sa1);
;                 sa0 += dpp_f<0x141>(sa0); sa1 += dpp_f<0x141>(sa1);
;                 const f32x2 saA = {sa0, sa0}, saB = {sa1, sa1}, vA = {v01.x, v01.x}, vB = {v01.y, v01.y};
;                 f32x2 yA, yB;
; #pragma unroll
;                 for (int j = 0; j < 4; ++j) {
;                     f32x2 tA = vA * m2[j], tB = vB * m2[j];
;                     tA = saA * b2[j] + tA; tB = saB * b2[j] + tB;
;                     s[0][j] = s[0][j] * w2[j] + tA; s[1][j] = s[1][j] * w2[j] + tB;
	v_pk_mul_f32 v[20:21], v[2:3], v[110:111] op_sel_hi:[1,0]
	v_pk_mul_f32 v[22:23], v[10:11], v[114:115] op_sel_hi:[1,0]
	v_pk_fma_f32 v[20:21], v[4:5], v[110:111], v[20:21] op_sel:[0,1,0]
	v_pk_fma_f32 v[22:23], v[12:13], v[114:115], v[22:23] op_sel:[0,1,0]
	v_pk_fma_f32 v[20:21], v[6:7], v[112:113], v[20:21] op_sel_hi:[1,0,1]
	v_pk_fma_f32 v[22:23], v[14:15], v[116:117], v[22:23] op_sel_hi:[1,0,1]
	v_pk_fma_f32 v[20:21], v[8:9], v[112:113], v[20:21] op_sel:[0,1,0]
	v_pk_fma_f32 v[22:23], v[16:17], v[116:117], v[22:23] op_sel:[0,1,0]
	v_add_f32_dpp v40, v40, v40 quad_perm:[1,0,3,2] row_mask:0xf bank_mask:0xf bound_ctrl:1
	v_pk_add_f32 v[20:21], v[20:21], v[22:23]
	v_add_f32_dpp v41, v41, v41 quad_perm:[1,0,3,2] row_mask:0xf bank_mask:0xf bound_ctrl:1
	v_add_f32_dpp v40, v40, v40 quad_perm:[2,3,0,1] row_mask:0xf bank_mask:0xf bound_ctrl:1
	v_pk_mul_f32 v[24:25], v[150:151], v[134:135] op_sel_hi:[1,0]
	v_add_f32_dpp v41, v41, v41 quad_perm:[2,3,0,1] row_mask:0xf bank_mask:0xf bound_ctrl:1
	v_add_f32_dpp v40, v40, v40 row_half_mirror row_mask:0xf bank_mask:0xf bound_ctrl:1
	v_pk_fma_f32 v[24:25], v[2:3], v[118:119], v[24:25] op_sel_hi:[1,0,1]
	v_add_f32_dpp v41, v41, v41 row_half_mirror row_mask:0xf bank_mask:0xf bound_ctrl:1
	v_pk_mul_f32 v[26:27], v[150:151], v[134:135] op_sel:[0,1]
	s_mov_b64 exec, vcc
	ds_write_b64 v181, v[40:41] offset:30208
	s_mov_b64 exec, s[12:13]
	v_pk_fma_f32 v[26:27], v[4:5], v[118:119], v[26:27] op_sel:[0,1,0]
	v_pk_mul_f32 v[28:29], v[150:151], v[136:137] op_sel_hi:[1,0]
	v_pk_mul_f32 v[30:31], v[150:151], v[136:137] op_sel:[0,1]
	v_pk_fma_f32 v[28:29], v[6:7], v[120:121], v[28:29] op_sel_hi:[1,0,1]
	v_pk_fma_f32 v[30:31], v[8:9], v[120:121], v[30:31] op_sel:[0,1,0]
	v_add_f32_dpp v20, v20, v20 quad_perm:[1,0,3,2] row_mask:0xf bank_mask:0xf bound_ctrl:1
	v_add_f32_dpp v21, v21, v21 quad_perm:[1,0,3,2] row_mask:0xf bank_mask:0xf bound_ctrl:1
	v_pk_mul_f32 v[32:33], v[150:151], v[138:139] op_sel_hi:[1,0]
	v_add_f32_dpp v20, v20, v20 quad_perm:[2,3,0,1] row_mask:0xf bank_mask:0xf bound_ctrl:1
	v_add_f32_dpp v21, v21, v21 quad_perm:[2,3,0,1] row_mask:0xf bank_mask:0xf bound_ctrl:1
	v_pk_fma_f32 v[32:33], v[10:11], v[122:123], v[32:33] op_sel_hi:[1,0,1]
	v_add_f32_dpp v20, v20, v20 row_half_mirror row_mask:0xf bank_mask:0xf bound_ctrl:1
	v_add_f32_dpp v21, v21, v21 row_half_mirror row_mask:0xf bank_mask:0xf bound_ctrl:1
	v_pk_mul_f32 v[34:35], v[150:151], v[138:139] op_sel:[0,1]
	v_pk_fma_f32 v[2:3], v[20:21], v[126:127], v[24:25] op_sel_hi:[1,0,1]
	v_pk_fma_f32 v[10:11], v[20:21], v[130:131], v[32:33] op_sel_hi:[1,0,1]
	v_pk_fma_f32 v[4:5], v[20:21], v[126:127], v[26:27] op_sel:[0,1,0]
	v_pk_fma_f32 v[6:7], v[20:21], v[128:129], v[28:29] op_sel_hi:[1,0,1]
	v_pk_fma_f32 v[8:9], v[20:21], v[128:129], v[30:31] op_sel:[0,1,0]
	v_pk_fma_f32 v[34:35], v[12:13], v[122:123], v[34:35] op_sel:[0,1,0]
	v_pk_mul_f32 v[36:37], v[150:151], v[140:141] op_sel_hi:[1,0]
	v_pk_fma_f32 v[12:13], v[20:21], v[130:131], v[34:35] op_sel:[0,1,0]
	v_pk_fma_f32 v[36:37], v[14:15], v[124:125], v[36:37] op_sel_hi:[1,0,1]
	v_pk_mul_f32 v[38:39], v[150:151], v[140:141] op_sel:[0,1]
	v_pk_fma_f32 v[14:15], v[20:21], v[132:133], v[36:37] op_sel_hi:[1,0,1]
	v_pk_fma_f32 v[38:39], v[16:17], v[124:125], v[38:39] op_sel:[0,1,0]
	v_pk_mul_f32 v[42:43], v[2:3], v[142:143] op_sel_hi:[1,0]
	v_pk_fma_f32 v[16:17], v[20:21], v[132:133], v[38:39] op_sel:[0,1,0]
	v_pk_mul_f32 v[44:45], v[10:11], v[146:147] op_sel_hi:[1,0]
	v_pk_fma_f32 v[42:43], v[4:5], v[142:143], v[42:43] op_sel:[0,1,0]
	v_pk_fma_f32 v[44:45], v[12:13], v[146:147], v[44:45] op_sel:[0,1,0]
	v_pk_fma_f32 v[42:43], v[6:7], v[144:145], v[42:43] op_sel_hi:[1,0,1]
	v_pk_fma_f32 v[44:45], v[14:15], v[148:149], v[44:45] op_sel_hi:[1,0,1]
	v_pk_fma_f32 v[42:43], v[8:9], v[144:145], v[42:43] op_sel:[0,1,0]
	v_pk_fma_f32 v[44:45], v[16:17], v[148:149], v[44:45] op_sel:[0,1,0]
	v_pk_add_f32 v[42:43], v[42:43], v[44:45]
	ds_read_b128 v[110:113], v180 offset:6400
	ds_read_b128 v[114:117], v180 offset:6416
	ds_read_b64 v[150:151], v181 offset:22784
	ds_read_b128 v[134:137], v180 offset:14592
	ds_read_b128 v[138:141], v180 offset:14608
	ds_read_b128 v[118:121], v180 offset:2304
	ds_read_b128 v[122:125], v180 offset:2320
	ds_read_b128 v[126:129], v180 offset:10496
	ds_read_b128 v[130:133], v180 offset:10512
	ds_read_b128 v[142:145], v180 offset:18688
	ds_read_b128 v[146:149], v180 offset:18704
	s_waitcnt lgkmcnt(11)
; __device__ __forceinline__ void rwkv_block(KP p, int o, int b, int hd, LAS unsigned char* lds, const bf16_t* P, bf16_t* YB) {
;     ...
;             for (int tt = 0; tt < 16; ++tt) {
;                 const int o8 = tt * 64 + c * 8;
;                 const f32x4 ka = *(const LAS f32x4*)(KK + o8), kb = *(const LAS f32x4*)(KK + o8 + 4);
;                 const f32x4 wa = *(const LAS f32x4*)(Wd + o8), wb = *(const LAS f32x4*)(Wd + o8 + 4);
;                 const f32x4 ba = *(const LAS f32x4*)(BB + o8), bb = *(const LAS f32x4*)(BB + o8 + 4);
;                 const f32x4 ma = *(const LAS f32x4*)(KM + o8), mb = *(const LAS f32x4*)(KM + o8 + 4);
;                 const f32x4 ra = *(const LAS f32x4*)(Rr + o8), rb = *(const LAS f32x4*)(Rr + o8 + 4);
;                 const f32x2 v01 = *(const LAS f32x2*)(Vv + tt * 64 + 2 * rp);
;                 const f32x2 k2[4] = {{ka[0], ka[1]}, {ka[2], ka[3]}, {kb[0], kb[1]}, {kb[2], kb[3]}};
;                 const f32x2 w2[4] = {{wa[0], wa[1]}, {wa[2], wa[3]}, {wb[0], wb[1]}, {wb[2], wb[3]}};
;                 const f32x2 b2[4] = {{ba[0], ba[1]}, {ba[2], ba[3]}, {bb[0], bb[1]}, {bb[2], bb[3]}};
;                 const f32x2 m2[4] = {{ma[0], ma[1]}, {ma[2], ma[3]}, {mb[0], mb[1]}, {mb[2], mb[3]}};
;                 const f32x2 r2[4] = {{ra[0], ra[1]}, {ra[2], ra[3]}, {rb[0], rb[1]}, {rb[2], rb[3]}};
;                 f32x2 accA = s[0][0] * k2[0], accB = s[1][0] * k2[0], accA2 = s[0][2] * k2[2], accB2 = s[1][2] * k2[2];
;                 accA = s[0][1] * k2[1] + accA; accB = s[1][1] * k2[1] + accB; accA2 = s[0][3] * k2[3] + accA2; accB2 = s[1][3] * k2[3] + accB2;
;                 accA = accA + accA2; accB = accB + accB2;
;                 float sa0 = accA.x + accA.y, sa1 = accB.x + accB.y;
;                 sa0 += dpp_f<0xB1>(sa0); sa1 += dpp_f<0xB1>(sa1);
;                 sa0 += dpp_f<0x4E>(sa0); sa1 += dpp_f<0x4E>(sa1);
;                 sa0 += dpp_f<0x141>(sa0); sa1 += dpp_f<0x141>(sa1);
;                 const f32x2 saA = {sa0, sa0}, saB = {sa1, sa1}, vA = {v01.x, v01.x}, vB = {v01.y, v01.y};
;                 f32x2 yA, yB;
; #pragma unroll
;                 for (int j = 0; j < 4; ++j) {
;                     f32x2 tA = vA * m2[j], tB = vB * m2[j];
;                     tA = saA * b2[j] + tA; tB = saB * b2[j] + tB;
;                     s[0][j] = s[0][j] * w2[j] + tA; s[1][j] = s[1][j] * w2[j] + tB;
	v_pk_mul_f32 v[20:21], v[2:3], v[64:65] op_sel_hi:[1,0]
	v_pk_mul_f32 v[22:23], v[10:11], v[68:69] op_sel_hi:[1,0]
	v_pk_fma_f32 v[20:21], v[4:5], v[64:65], v[20:21] op_sel:[0,1,0]
	v_pk_fma_f32 v[22:23], v[12:13], v[68:69], v[22:23] op_sel:[0,1,0]
	v_pk_fma_f32 v[20:21], v[6:7], v[66:67], v[20:21] op_sel_hi:[1,0,1]
	v_pk_fma_f32 v[22:23], v[14:15], v[70:71], v[22:23] op_sel_hi:[1,0,1]
	v_pk_fma_f32 v[20:21], v[8:9], v[66:67], v[20:21] op_sel:[0,1,0]
	v_pk_fma_f32 v[22:23], v[16:17], v[70:71], v[22:23] op_sel:[0,1,0]
	v_add_f32_dpp v42, v42, v42 quad_perm:[1,0,3,2] row_mask:0xf bank_mask:0xf bound_ctrl:1
	v_pk_add_f32 v[20:21], v[20:21], v[22:23]
	v_add_f32_dpp v43, v43, v43 quad_perm:[1,0,3,2] row_mask:0xf bank_mask:0xf bound_ctrl:1
	v_add_f32_dpp v42, v42, v42 quad_perm:[2,3,0,1] row_mask:0xf bank_mask:0xf bound_ctrl:1
	v_pk_mul_f32 v[24:25], v[104:105], v[88:89] op_sel_hi:[1,0]
	v_add_f32_dpp v43, v43, v43 quad_perm:[2,3,0,1] row_mask:0xf bank_mask:0xf bound_ctrl:1
	v_add_f32_dpp v42, v42, v42 row_half_mirror row_mask:0xf bank_mask:0xf bound_ctrl:1
	v_pk_fma_f32 v[24:25], v[2:3], v[72:73], v[24:25] op_sel_hi:[1,0,1]
	v_add_f32_dpp v43, v43, v43 row_half_mirror row_mask:0xf bank_mask:0xf bound_ctrl:1
	v_pk_mul_f32 v[26:27], v[104:105], v[88:89] op_sel:[0,1]
	s_mov_b64 exec, vcc
	ds_write_b64 v181, v[42:43] offset:30464
	s_mov_b64 exec, s[12:13]
	v_pk_fma_f32 v[26:27], v[4:5], v[72:73], v[26:27] op_sel:[0,1,0]
	v_pk_mul_f32 v[28:29], v[104:105], v[90:91] op_sel_hi:[1,0]
	v_pk_mul_f32 v[30:31], v[104:105], v[90:91] op_sel:[0,1]
	v_pk_fma_f32 v[28:29], v[6:7], v[74:75], v[28:29] op_sel_hi:[1,0,1]
	v_pk_fma_f32 v[30:31], v[8:9], v[74:75], v[30:31] op_sel:[0,1,0]
	v_add_f32_dpp v20, v20, v20 quad_perm:[1,0,3,2] row_mask:0xf bank_mask:0xf bound_ctrl:1
	v_add_f32_dpp v21, v21, v21 quad_perm:[1,0,3,2] row_mask:0xf bank_mask:0xf bound_ctrl:1
	v_pk_mul_f32 v[32:33], v[104:105], v[92:93] op_sel_hi:[1,0]
	v_add_f32_dpp v20, v20, v20 quad_perm:[2,3,0,1] row_mask:0xf bank_mask:0xf bound_ctrl:1
	v_add_f32_dpp v21, v21, v21 quad_perm:[2,3,0,1] row_mask:0xf bank_mask:0xf bound_ctrl:1
	v_pk_fma_f32 v[32:33], v[10:11], v[76:77], v[32:33] op_sel_hi:[1,0,1]
	v_add_f32_dpp v20, v20, v20 row_half_mirror row_mask:0xf bank_mask:0xf bound_ctrl:1
	v_add_f32_dpp v21, v21, v21 row_half_mirror row_mask:0xf bank_mask:0xf bound_ctrl:1
	v_pk_mul_f32 v[34:35], v[104:105], v[92:93] op_sel:[0,1]
	v_pk_fma_f32 v[2:3], v[20:21], v[80:81], v[24:25] op_sel_hi:[1,0,1]
	v_pk_fma_f32 v[10:11], v[20:21], v[84:85], v[32:33] op_sel_hi:[1,0,1]
	v_pk_fma_f32 v[4:5], v[20:21], v[80:81], v[26:27] op_sel:[0,1,0]
	v_pk_fma_f32 v[6:7], v[20:21], v[82:83], v[28:29] op_sel_hi:[1,0,1]
	v_pk_fma_f32 v[8:9], v[20:21], v[82:83], v[30:31] op_sel:[0,1,0]
	v_pk_fma_f32 v[34:35], v[12:13], v[76:77], v[34:35] op_sel:[0,1,0]
	v_pk_mul_f32 v[36:37], v[104:105], v[94:95] op_sel_hi:[1,0]
	v_pk_fma_f32 v[12:13], v[20:21], v[84:85], v[34:35] op_sel:[0,1,0]
	v_pk_fma_f32 v[36:37], v[14:15], v[78:79], v[36:37] op_sel_hi:[1,0,1]
	v_pk_mul_f32 v[38:39], v[104:105], v[94:95] op_sel:[0,1]
	v_pk_fma_f32 v[14:15], v[20:21], v[86:87], v[36:37] op_sel_hi:[1,0,1]
	v_pk_fma_f32 v[38:39], v[16:17], v[78:79], v[38:39] op_sel:[0,1,0]
	v_pk_mul_f32 v[40:41], v[2:3], v[96:97] op_sel_hi:[1,0]
	v_pk_fma_f32 v[16:17], v[20:21], v[86:87], v[38:39] op_sel:[0,1,0]
	v_pk_mul_f32 v[44:45], v[10:11], v[100:101] op_sel_hi:[1,0]
	v_pk_fma_f32 v[40:41], v[4:5], v[96:97], v[40:41] op_sel:[0,1,0]
	v_pk_fma_f32 v[44:45], v[12:13], v[100:101], v[44:45] op_sel:[0,1,0]
	v_pk_fma_f32 v[40:41], v[6:7], v[98:99], v[40:41] op_sel_hi:[1,0,1]
	v_pk_fma_f32 v[44:45], v[14:15], v[102:103], v[44:45] op_sel_hi:[1,0,1]
	v_pk_fma_f32 v[40:41], v[8:9], v[98:99], v[40:41] op_sel:[0,1,0]
	v_pk_fma_f32 v[44:45], v[16:17], v[102:103], v[44:45] op_sel:[0,1,0]
	v_pk_add_f32 v[40:41], v[40:41], v[44:45]
	ds_read_b128 v[64:67], v180 offset:6656
	ds_read_b128 v[68:71], v180 offset:6672
	ds_read_b64 v[104:105], v181 offset:23040
	ds_read_b128 v[88:91], v180 offset:14848
	ds_read_b128 v[92:95], v180 offset:14864
	ds_read_b128 v[72:75], v180 offset:2560
	ds_read_b128 v[76:79], v180 offset:2576
	ds_read_b128 v[80:83], v180 offset:10752
	ds_read_b128 v[84:87], v180 offset:10768
	ds_read_b128 v[96:99], v180 offset:18944
	ds_read_b128 v[100:103], v180 offset:18960
	s_waitcnt lgkmcnt(11)
; __device__ __forceinline__ void rwkv_block(KP p, int o, int b, int hd, LAS unsigned char* lds, const bf16_t* P, bf16_t* YB) {
;     ...
;             for (int tt = 0; tt < 16; ++tt) {
;                 const int o8 = tt * 64 + c * 8;
;                 const f32x4 ka = *(const LAS f32x4*)(KK + o8), kb = *(const LAS f32x4*)(KK + o8 + 4);
;                 const f32x4 wa = *(const LAS f32x4*)(Wd + o8), wb = *(const LAS f32x4*)(Wd + o8 + 4);
;                 const f32x4 ba = *(const LAS f32x4*)(BB + o8), bb = *(const LAS f32x4*)(BB + o8 + 4);
;                 const f32x4 ma = *(const LAS f32x4*)(KM + o8), mb = *(const LAS f32x4*)(KM + o8 + 4);
;                 const f32x4 ra = *(const LAS f32x4*)(Rr + o8), rb = *(const LAS f32x4*)(Rr + o8 + 4);
;                 const f32x2 v01 = *(const LAS f32x2*)(Vv + tt * 64 + 2 * rp);
;                 const f32x2 k2[4] = {{ka[0], ka[1]}, {ka[2], ka[3]}, {kb[0], kb[1]}, {kb[2], kb[3]}};
;                 const f32x2 w2[4] = {{wa[0], wa[1]}, {wa[2], wa[3]}, {wb[0], wb[1]}, {wb[2], wb[3]}};
;                 const f32x2 b2[4] = {{ba[0], ba[1]}, {ba[2], ba[3]}, {bb[0], bb[1]}, {bb[2], bb[3]}};
;                 const f32x2 m2[4] = {{ma[0], ma[1]}, {ma[2], ma[3]}, {mb[0], mb[1]}, {mb[2], mb[3]}};
;                 const f32x2 r2[4] = {{ra[0], ra[1]}, {ra[2], ra[3]}, {rb[0], rb[1]}, {rb[2], rb[3]}};
;                 f32x2 accA = s[0][0] * k2[0], accB = s[1][0] * k2[0], accA2 = s[0][2] * k2[2], accB2 = s[1][2] * k2[2];
;                 accA = s[0][1] * k2[1] + accA; accB = s[1][1] * k2[1] + accB; accA2 = s[0][3] * k2[3] + accA2; accB2 = s[1][3] * k2[3] + accB2;
;                 accA = accA + accA2; accB = accB + accB2;
;                 float sa0 = accA.x + accA.y, sa1 = accB.x + accB.y;
;                 sa0 += dpp_f<0xB1>(sa0); sa1 += dpp_f<0xB1>(sa1);
;                 sa0 += dpp_f<0x4E>(sa0); sa1 += dpp_f<0x4E>(sa1);
;                 sa0 += dpp_f<0x141>(sa0); sa1 += dpp_f<0x141>(sa1);
;                 const f32x2 saA = {sa0, sa0}, saB = {sa1, sa1}, vA = {v01.x, v01.x}, vB = {v01.y, v01.y};
;                 f32x2 yA, yB;
; #pragma unroll
;                 for (int j = 0; j < 4; ++j) {
;                     f32x2 tA = vA * m2[j], tB = vB * m2[j];
;                     tA = saA * b2[j] + tA; tB = saB * b2[j] + tB;
;                     s[0][j] = s[0][j] * w2[j] + tA; s[1][j] = s[1][j] * w2[j] + tB;
	v_pk_mul_f32 v[20:21], v[2:3], v[110:111] op_sel_hi:[1,0]
	v_pk_mul_f32 v[22:23], v[10:11], v[114:115] op_sel_hi:[1,0]
	v_pk_fma_f32 v[20:21], v[4:5], v[110:111], v[20:21] op_sel:[0,1,0]
	v_pk_fma_f32 v[22:23], v[12:13], v[114:115], v[22:23] op_sel:[0,1,0]
	v_pk_fma_f32 v[20:21], v[6:7], v[112:113], v[20:21] op_sel_hi:[1,0,1]
	v_pk_fma_f32 v[22:23], v[14:15], v[116:117], v[22:23] op_sel_hi:[1,0,1]
	v_pk_fma_f32 v[20:21], v[8:9], v[112:113], v[20:21] op_sel:[0,1,0]
	v_pk_fma_f32 v[22:23], v[16:17], v[116:117], v[22:23] op_sel:[0,1,0]
	v_add_f32_dpp v40, v40, v40 quad_perm:[1,0,3,2] row_mask:0xf bank_mask:0xf bound_ctrl:1
	v_pk_add_f32 v[20:21], v[20:21], v[22:23]
	v_add_f32_dpp v41, v41, v41 quad_perm:[1,0,3,2] row_mask:0xf bank_mask:0xf bound_ctrl:1
	v_add_f32_dpp v40, v40, v40 quad_perm:[2,3,0,1] row_mask:0xf bank_mask:0xf bound_ctrl:1
	v_pk_mul_f32 v[24:25], v[150:151], v[134:135] op_sel_hi:[1,0]
	v_add_f32_dpp v41, v41, v41 quad_perm:[2,3,0,1] row_mask:0xf bank_mask:0xf bound_ctrl:1
	v_add_f32_dpp v40, v40, v40 row_half_mirror row_mask:0xf bank_mask:0xf bound_ctrl:1
	v_pk_fma_f32 v[24:25], v[2:3], v[118:119], v[24:25] op_sel_hi:[1,0,1]
	v_add_f32_dpp v41, v41, v41 row_half_mirror row_mask:0xf bank_mask:0xf bound_ctrl:1
	v_pk_mul_f32 v[26:27], v[150:151], v[134:135] op_sel:[0,1]
	s_mov_b64 exec, vcc
	ds_write_b64 v181, v[40:41] offset:30720
	s_mov_b64 exec, s[12:13]
	v_pk_fma_f32 v[26:27], v[4:5], v[118:119], v[26:27] op_sel:[0,1,0]
	v_pk_mul_f32 v[28:29], v[150:151], v[136:137] op_sel_hi:[1,0]
	v_pk_mul_f32 v[30:31], v[150:151], v[136:137] op_sel:[0,1]
	v_pk_fma_f32 v[28:29], v[6:7], v[120:121], v[28:29] op_sel_hi:[1,0,1]
	v_pk_fma_f32 v[30:31], v[8:9], v[120:121], v[30:31] op_sel:[0,1,0]
	v_add_f32_dpp v20, v20, v20 quad_perm:[1,0,3,2] row_mask:0xf bank_mask:0xf bound_ctrl:1
	v_add_f32_dpp v21, v21, v21 quad_perm:[1,0,3,2] row_mask:0xf bank_mask:0xf bound_ctrl:1
	v_pk_mul_f32 v[32:33], v[150:151], v[138:139] op_sel_hi:[1,0]
	v_add_f32_dpp v20, v20, v20 quad_perm:[2,3,0,1] row_mask:0xf bank_mask:0xf bound_ctrl:1
	v_add_f32_dpp v21, v21, v21 quad_perm:[2,3,0,1] row_mask:0xf bank_mask:0xf bound_ctrl:1
	v_pk_fma_f32 v[32:33], v[10:11], v[122:123], v[32:33] op_sel_hi:[1,0,1]
	v_add_f32_dpp v20, v20, v20 row_half_mirror row_mask:0xf bank_mask:0xf bound_ctrl:1
	v_add_f32_dpp v21, v21, v21 row_half_mirror row_mask:0xf bank_mask:0xf bound_ctrl:1
	v_pk_mul_f32 v[34:35], v[150:151], v[138:139] op_sel:[0,1]
	v_pk_fma_f32 v[2:3], v[20:21], v[126:127], v[24:25] op_sel_hi:[1,0,1]
	v_pk_fma_f32 v[10:11], v[20:21], v[130:131], v[32:33] op_sel_hi:[1,0,1]
	v_pk_fma_f32 v[4:5], v[20:21], v[126:127], v[26:27] op_sel:[0,1,0]
	v_pk_fma_f32 v[6:7], v[20:21], v[128:129], v[28:29] op_sel_hi:[1,0,1]
	v_pk_fma_f32 v[8:9], v[20:21], v[128:129], v[30:31] op_sel:[0,1,0]
	v_pk_fma_f32 v[34:35], v[12:13], v[122:123], v[34:35] op_sel:[0,1,0]
	v_pk_mul_f32 v[36:37], v[150:151], v[140:141] op_sel_hi:[1,0]
	v_pk_fma_f32 v[12:13], v[20:21], v[130:131], v[34:35] op_sel:[0,1,0]
	v_pk_fma_f32 v[36:37], v[14:15], v[124:125], v[36:37] op_sel_hi:[1,0,1]
	v_pk_mul_f32 v[38:39], v[150:151], v[140:141] op_sel:[0,1]
	v_pk_fma_f32 v[14:15], v[20:21], v[132:133], v[36:37] op_sel_hi:[1,0,1]
	v_pk_fma_f32 v[38:39], v[16:17], v[124:125], v[38:39] op_sel:[0,1,0]
	v_pk_mul_f32 v[42:43], v[2:3], v[142:143] op_sel_hi:[1,0]
	v_pk_fma_f32 v[16:17], v[20:21], v[132:133], v[38:39] op_sel:[0,1,0]
	v_pk_mul_f32 v[44:45], v[10:11], v[146:147] op_sel_hi:[1,0]
	v_pk_fma_f32 v[42:43], v[4:5], v[142:143], v[42:43] op_sel:[0,1,0]
	v_pk_fma_f32 v[44:45], v[12:13], v[146:147], v[44:45] op_sel:[0,1,0]
	v_pk_fma_f32 v[42:43], v[6:7], v[144:145], v[42:43] op_sel_hi:[1,0,1]
	v_pk_fma_f32 v[44:45], v[14:15], v[148:149], v[44:45] op_sel_hi:[1,0,1]
	v_pk_fma_f32 v[42:43], v[8:9], v[144:145], v[42:43] op_sel:[0,1,0]
	v_pk_fma_f32 v[44:45], v[16:17], v[148:149], v[44:45] op_sel:[0,1,0]
	v_pk_add_f32 v[42:43], v[42:43], v[44:45]
	ds_read_b128 v[110:113], v180 offset:6912
	ds_read_b128 v[114:117], v180 offset:6928
	ds_read_b64 v[150:151], v181 offset:23296
	ds_read_b128 v[134:137], v180 offset:15104
	ds_read_b128 v[138:141], v180 offset:15120
	ds_read_b128 v[118:121], v180 offset:2816
	ds_read_b128 v[122:125], v180 offset:2832
	ds_read_b128 v[126:129], v180 offset:11008
	ds_read_b128 v[130:133], v180 offset:11024
	ds_read_b128 v[142:145], v180 offset:19200
	ds_read_b128 v[146:149], v180 offset:19216
	s_waitcnt lgkmcnt(11)
; __device__ __forceinline__ void rwkv_block(KP p, int o, int b, int hd, LAS unsigned char* lds, const bf16_t* P, bf16_t* YB) {
;     ...
;             for (int tt = 0; tt < 16; ++tt) {
;                 const int o8 = tt * 64 + c * 8;
;                 const f32x4 ka = *(const LAS f32x4*)(KK + o8), kb = *(const LAS f32x4*)(KK + o8 + 4);
;                 const f32x4 wa = *(const LAS f32x4*)(Wd + o8), wb = *(const LAS f32x4*)(Wd + o8 + 4);
;                 const f32x4 ba = *(const LAS f32x4*)(BB + o8), bb = *(const LAS f32x4*)(BB + o8 + 4);
;                 const f32x4 ma = *(const LAS f32x4*)(KM + o8), mb = *(const LAS f32x4*)(KM + o8 + 4);
;                 const f32x4 ra = *(const LAS f32x4*)(Rr + o8), rb = *(const LAS f32x4*)(Rr + o8 + 4);
;                 const f32x2 v01 = *(const LAS f32x2*)(Vv + tt * 64 + 2 * rp);
;                 const f32x2 k2[4] = {{ka[0], ka[1]}, {ka[2], ka[3]}, {kb[0], kb[1]}, {kb[2], kb[3]}};
;                 const f32x2 w2[4] = {{wa[0], wa[1]}, {wa[2], wa[3]}, {wb[0], wb[1]}, {wb[2], wb[3]}};
;                 const f32x2 b2[4] = {{ba[0], ba[1]}, {ba[2], ba[3]}, {bb[0], bb[1]}, {bb[2], bb[3]}};
;                 const f32x2 m2[4] = {{ma[0], ma[1]}, {ma[2], ma[3]}, {mb[0], mb[1]}, {mb[2], mb[3]}};
;                 const f32x2 r2[4] = {{ra[0], ra[1]}, {ra[2], ra[3]}, {rb[0], rb[1]}, {rb[2], rb[3]}};
;                 f32x2 accA = s[0][0] * k2[0], accB = s[1][0] * k2[0], accA2 = s[0][2] * k2[2], accB2 = s[1][2] * k2[2];
;                 accA = s[0][1] * k2[1] + accA; accB = s[1][1] * k2[1] + accB; accA2 = s[0][3] * k2[3] + accA2; accB2 = s[1][3] * k2[3] + accB2;
;                 accA = accA + accA2; accB = accB + accB2;
;                 float sa0 = accA.x + accA.y, sa1 = accB.x + accB.y;
;                 sa0 += dpp_f<0xB1>(sa0); sa1 += dpp_f<0xB1>(sa1);
;                 sa0 += dpp_f<0x4E>(sa0); sa1 += dpp_f<0x4E>(sa1);
;                 sa0 += dpp_f<0x141>(sa0); sa1 += dpp_f<0x141>(sa1);
;                 const f32x2 saA = {sa0, sa0}, saB = {sa1, sa1}, vA = {v01.x, v01.x}, vB = {v01.y, v01.y};
;                 f32x2 yA, yB;
; #pragma unroll
;                 for (int j = 0; j < 4; ++j) {
;                     f32x2 tA = vA * m2[j], tB = vB * m2[j];
;                     tA = saA * b2[j] + tA; tB = saB * b2[j] + tB;
;                     s[0][j] = s[0][j] * w2[j] + tA; s[1][j] = s[1][j] * w2[j] + tB;
	v_pk_mul_f32 v[20:21], v[2:3], v[64:65] op_sel_hi:[1,0]
	v_pk_mul_f32 v[22:23], v[10:11], v[68:69] op_sel_hi:[1,0]
	v_pk_fma_f32 v[20:21], v[4:5], v[64:65], v[20:21] op_sel:[0,1,0]
	v_pk_fma_f32 v[22:23], v[12:13], v[68:69], v[22:23] op_sel:[0,1,0]
	v_pk_fma_f32 v[20:21], v[6:7], v[66:67], v[20:21] op_sel_hi:[1,0,1]
	v_pk_fma_f32 v[22:23], v[14:15], v[70:71], v[22:23] op_sel_hi:[1,0,1]
	v_pk_fma_f32 v[20:21], v[8:9], v[66:67], v[20:21] op_sel:[0,1,0]
	v_pk_fma_f32 v[22:23], v[16:17], v[70:71], v[22:23] op_sel:[0,1,0]
	v_add_f32_dpp v42, v42, v42 quad_perm:[1,0,3,2] row_mask:0xf bank_mask:0xf bound_ctrl:1
	v_pk_add_f32 v[20:21], v[20:21], v[22:23]
	v_add_f32_dpp v43, v43, v43 quad_perm:[1,0,3,2] row_mask:0xf bank_mask:0xf bound_ctrl:1
	v_add_f32_dpp v42, v42, v42 quad_perm:[2,3,0,1] row_mask:0xf bank_mask:0xf bound_ctrl:1
	v_pk_mul_f32 v[24:25], v[104:105], v[88:89] op_sel_hi:[1,0]
	v_add_f32_dpp v43, v43, v43 quad_perm:[2,3,0,1] row_mask:0xf bank_mask:0xf bound_ctrl:1
	v_add_f32_dpp v42, v42, v42 row_half_mirror row_mask:0xf bank_mask:0xf bound_ctrl:1
	v_pk_fma_f32 v[24:25], v[2:3], v[72:73], v[24:25] op_sel_hi:[1,0,1]
	v_add_f32_dpp v43, v43, v43 row_half_mirror row_mask:0xf bank_mask:0xf bound_ctrl:1
	v_pk_mul_f32 v[26:27], v[104:105], v[88:89] op_sel:[0,1]
	s_mov_b64 exec, vcc
	ds_write_b64 v181, v[42:43] offset:30976
	s_mov_b64 exec, s[12:13]
	v_pk_fma_f32 v[26:27], v[4:5], v[72:73], v[26:27] op_sel:[0,1,0]
	v_pk_mul_f32 v[28:29], v[104:105], v[90:91] op_sel_hi:[1,0]
	v_pk_mul_f32 v[30:31], v[104:105], v[90:91] op_sel:[0,1]
	v_pk_fma_f32 v[28:29], v[6:7], v[74:75], v[28:29] op_sel_hi:[1,0,1]
	v_pk_fma_f32 v[30:31], v[8:9], v[74:75], v[30:31] op_sel:[0,1,0]
	v_add_f32_dpp v20, v20, v20 quad_perm:[1,0,3,2] row_mask:0xf bank_mask:0xf bound_ctrl:1
	v_add_f32_dpp v21, v21, v21 quad_perm:[1,0,3,2] row_mask:0xf bank_mask:0xf bound_ctrl:1
	v_pk_mul_f32 v[32:33], v[104:105], v[92:93] op_sel_hi:[1,0]
	v_add_f32_dpp v20, v20, v20 quad_perm:[2,3,0,1] row_mask:0xf bank_mask:0xf bound_ctrl:1
	v_add_f32_dpp v21, v21, v21 quad_perm:[2,3,0,1] row_mask:0xf bank_mask:0xf bound_ctrl:1
	v_pk_fma_f32 v[32:33], v[10:11], v[76:77], v[32:33] op_sel_hi:[1,0,1]
	v_add_f32_dpp v20, v20, v20 row_half_mirror row_mask:0xf bank_mask:0xf bound_ctrl:1
	v_add_f32_dpp v21, v21, v21 row_half_mirror row_mask:0xf bank_mask:0xf bound_ctrl:1
	v_pk_mul_f32 v[34:35], v[104:105], v[92:93] op_sel:[0,1]
	v_pk_fma_f32 v[2:3], v[20:21], v[80:81], v[24:25] op_sel_hi:[1,0,1]
	v_pk_fma_f32 v[10:11], v[20:21], v[84:85], v[32:33] op_sel_hi:[1,0,1]
	v_pk_fma_f32 v[4:5], v[20:21], v[80:81], v[26:27] op_sel:[0,1,0]
	v_pk_fma_f32 v[6:7], v[20:21], v[82:83], v[28:29] op_sel_hi:[1,0,1]
	v_pk_fma_f32 v[8:9], v[20:21], v[82:83], v[30:31] op_sel:[0,1,0]
	v_pk_fma_f32 v[34:35], v[12:13], v[76:77], v[34:35] op_sel:[0,1,0]
	v_pk_mul_f32 v[36:37], v[104:105], v[94:95] op_sel_hi:[1,0]
	v_pk_fma_f32 v[12:13], v[20:21], v[84:85], v[34:35] op_sel:[0,1,0]
	v_pk_fma_f32 v[36:37], v[14:15], v[78:79], v[36:37] op_sel_hi:[1,0,1]
	v_pk_mul_f32 v[38:39], v[104:105], v[94:95] op_sel:[0,1]
	v_pk_fma_f32 v[14:15], v[20:21], v[86:87], v[36:37] op_sel_hi:[1,0,1]
	v_pk_fma_f32 v[38:39], v[16:17], v[78:79], v[38:39] op_sel:[0,1,0]
	v_pk_mul_f32 v[40:41], v[2:3], v[96:97] op_sel_hi:[1,0]
	v_pk_fma_f32 v[16:17], v[20:21], v[86:87], v[38:39] op_sel:[0,1,0]
	v_pk_mul_f32 v[44:45], v[10:11], v[100:101] op_sel_hi:[1,0]
	v_pk_fma_f32 v[40:41], v[4:5], v[96:97], v[40:41] op_sel:[0,1,0]
	v_pk_fma_f32 v[44:45], v[12:13], v[100:101], v[44:45] op_sel:[0,1,0]
	v_pk_fma_f32 v[40:41], v[6:7], v[98:99], v[40:41] op_sel_hi:[1,0,1]
	v_pk_fma_f32 v[44:45], v[14:15], v[102:103], v[44:45] op_sel_hi:[1,0,1]
	v_pk_fma_f32 v[40:41], v[8:9], v[98:99], v[40:41] op_sel:[0,1,0]
	v_pk_fma_f32 v[44:45], v[16:17], v[102:103], v[44:45] op_sel:[0,1,0]
	v_pk_add_f32 v[40:41], v[40:41], v[44:45]
	ds_read_b128 v[64:67], v180 offset:7168
	ds_read_b128 v[68:71], v180 offset:7184
	ds_read_b64 v[104:105], v181 offset:23552
	ds_read_b128 v[88:91], v180 offset:15360
	ds_read_b128 v[92:95], v180 offset:15376
	ds_read_b128 v[72:75], v180 offset:3072
	ds_read_b128 v[76:79], v180 offset:3088
	ds_read_b128 v[80:83], v180 offset:11264
	ds_read_b128 v[84:87], v180 offset:11280
	ds_read_b128 v[96:99], v180 offset:19456
	ds_read_b128 v[100:103], v180 offset:19472
	s_waitcnt lgkmcnt(11)
; __device__ __forceinline__ void rwkv_block(KP p, int o, int b, int hd, LAS unsigned char* lds, const bf16_t* P, bf16_t* YB) {
;     ...
;             for (int tt = 0; tt < 16; ++tt) {
;                 const int o8 = tt * 64 + c * 8;
;                 const f32x4 ka = *(const LAS f32x4*)(KK + o8), kb = *(const LAS f32x4*)(KK + o8 + 4);
;                 const f32x4 wa = *(const LAS f32x4*)(Wd + o8), wb = *(const LAS f32x4*)(Wd + o8 + 4);
;                 const f32x4 ba = *(const LAS f32x4*)(BB + o8), bb = *(const LAS f32x4*)(BB + o8 + 4);
;                 const f32x4 ma = *(const LAS f32x4*)(KM + o8), mb = *(const LAS f32x4*)(KM + o8 + 4);
;                 const f32x4 ra = *(const LAS f32x4*)(Rr + o8), rb = *(const LAS f32x4*)(Rr + o8 + 4);
;                 const f32x2 v01 = *(const LAS f32x2*)(Vv + tt * 64 + 2 * rp);
;                 const f32x2 k2[4] = {{ka[0], ka[1]}, {ka[2], ka[3]}, {kb[0], kb[1]}, {kb[2], kb[3]}};
;                 const f32x2 w2[4] = {{wa[0], wa[1]}, {wa[2], wa[3]}, {wb[0], wb[1]}, {wb[2], wb[3]}};
;                 const f32x2 b2[4] = {{ba[0], ba[1]}, {ba[2], ba[3]}, {bb[0], bb[1]}, {bb[2], bb[3]}};
;                 const f32x2 m2[4] = {{ma[0], ma[1]}, {ma[2], ma[3]}, {mb[0], mb[1]}, {mb[2], mb[3]}};
;                 const f32x2 r2[4] = {{ra[0], ra[1]}, {ra[2], ra[3]}, {rb[0], rb[1]}, {rb[2], rb[3]}};
;                 f32x2 accA = s[0][0] * k2[0], accB = s[1][0] * k2[0], accA2 = s[0][2] * k2[2], accB2 = s[1][2] * k2[2];
;                 accA = s[0][1] * k2[1] + accA; accB = s[1][1] * k2[1] + accB; accA2 = s[0][3] * k2[3] + accA2; accB2 = s[1][3] * k2[3] + accB2;
;                 accA = accA + accA2; accB = accB + accB2;
;                 float sa0 = accA.x + accA.y, sa1 = accB.x + accB.y;
;                 sa0 += dpp_f<0xB1>(sa0); sa1 += dpp_f<0xB1>(sa1);
;                 sa0 += dpp_f<0x4E>(sa0); sa1 += dpp_f<0x4E>(sa1);
;                 sa0 += dpp_f<0x141>(sa0); sa1 += dpp_f<0x141>(sa1);
;                 const f32x2 saA = {sa0, sa0}, saB = {sa1, sa1}, vA = {v01.x, v01.x}, vB = {v01.y, v01.y};
;                 f32x2 yA, yB;
; #pragma unroll
;                 for (int j = 0; j < 4; ++j) {
;                     f32x2 tA = vA * m2[j], tB = vB * m2[j];
;                     tA = saA * b2[j] + tA; tB = saB * b2[j] + tB;
;                     s[0][j] = s[0][j] * w2[j] + tA; s[1][j] = s[1][j] * w2[j] + tB;
	v_pk_mul_f32 v[20:21], v[2:3], v[110:111] op_sel_hi:[1,0]
	v_pk_mul_f32 v[22:23], v[10:11], v[114:115] op_sel_hi:[1,0]
	v_pk_fma_f32 v[20:21], v[4:5], v[110:111], v[20:21] op_sel:[0,1,0]
	v_pk_fma_f32 v[22:23], v[12:13], v[114:115], v[22:23] op_sel:[0,1,0]
	v_pk_fma_f32 v[20:21], v[6:7], v[112:113], v[20:21] op_sel_hi:[1,0,1]
	v_pk_fma_f32 v[22:23], v[14:15], v[116:117], v[22:23] op_sel_hi:[1,0,1]
	v_pk_fma_f32 v[20:21], v[8:9], v[112:113], v[20:21] op_sel:[0,1,0]
	v_pk_fma_f32 v[22:23], v[16:17], v[116:117], v[22:23] op_sel:[0,1,0]
	v_add_f32_dpp v40, v40, v40 quad_perm:[1,0,3,2] row_mask:0xf bank_mask:0xf bound_ctrl:1
	v_pk_add_f32 v[20:21], v[20:21], v[22:23]
	v_add_f32_dpp v41, v41, v41 quad_perm:[1,0,3,2] row_mask:0xf bank_mask:0xf bound_ctrl:1
	v_add_f32_dpp v40, v40, v40 quad_perm:[2,3,0,1] row_mask:0xf bank_mask:0xf bound_ctrl:1
	v_pk_mul_f32 v[24:25], v[150:151], v[134:135] op_sel_hi:[1,0]
	v_add_f32_dpp v41, v41, v41 quad_perm:[2,3,0,1] row_mask:0xf bank_mask:0xf bound_ctrl:1
	v_add_f32_dpp v40, v40, v40 row_half_mirror row_mask:0xf bank_mask:0xf bound_ctrl:1
	v_pk_fma_f32 v[24:25], v[2:3], v[118:119], v[24:25] op_sel_hi:[1,0,1]
	v_add_f32_dpp v41, v41, v41 row_half_mirror row_mask:0xf bank_mask:0xf bound_ctrl:1
	v_pk_mul_f32 v[26:27], v[150:151], v[134:135] op_sel:[0,1]
	s_mov_b64 exec, vcc
	ds_write_b64 v181, v[40:41] offset:31232
	s_mov_b64 exec, s[12:13]
	v_pk_fma_f32 v[26:27], v[4:5], v[118:119], v[26:27] op_sel:[0,1,0]
	v_pk_mul_f32 v[28:29], v[150:151], v[136:137] op_sel_hi:[1,0]
	v_pk_mul_f32 v[30:31], v[150:151], v[136:137] op_sel:[0,1]
	v_pk_fma_f32 v[28:29], v[6:7], v[120:121], v[28:29] op_sel_hi:[1,0,1]
	v_pk_fma_f32 v[30:31], v[8:9], v[120:121], v[30:31] op_sel:[0,1,0]
	v_add_f32_dpp v20, v20, v20 quad_perm:[1,0,3,2] row_mask:0xf bank_mask:0xf bound_ctrl:1
	v_add_f32_dpp v21, v21, v21 quad_perm:[1,0,3,2] row_mask:0xf bank_mask:0xf bound_ctrl:1
	v_pk_mul_f32 v[32:33], v[150:151], v[138:139] op_sel_hi:[1,0]
	v_add_f32_dpp v20, v20, v20 quad_perm:[2,3,0,1] row_mask:0xf bank_mask:0xf bound_ctrl:1
	v_add_f32_dpp v21, v21, v21 quad_perm:[2,3,0,1] row_mask:0xf bank_mask:0xf bound_ctrl:1
	v_pk_fma_f32 v[32:33], v[10:11], v[122:123], v[32:33] op_sel_hi:[1,0,1]
	v_add_f32_dpp v20, v20, v20 row_half_mirror row_mask:0xf bank_mask:0xf bound_ctrl:1
	v_add_f32_dpp v21, v21, v21 row_half_mirror row_mask:0xf bank_mask:0xf bound_ctrl:1
	v_pk_mul_f32 v[34:35], v[150:151], v[138:139] op_sel:[0,1]
	v_pk_fma_f32 v[2:3], v[20:21], v[126:127], v[24:25] op_sel_hi:[1,0,1]
	v_pk_fma_f32 v[10:11], v[20:21], v[130:131], v[32:33] op_sel_hi:[1,0,1]
	v_pk_fma_f32 v[4:5], v[20:21], v[126:127], v[26:27] op_sel:[0,1,0]
	v_pk_fma_f32 v[6:7], v[20:21], v[128:129], v[28:29] op_sel_hi:[1,0,1]
	v_pk_fma_f32 v[8:9], v[20:21], v[128:129], v[30:31] op_sel:[0,1,0]
	v_pk_fma_f32 v[34:35], v[12:13], v[122:123], v[34:35] op_sel:[0,1,0]
	v_pk_mul_f32 v[36:37], v[150:151], v[140:141] op_sel_hi:[1,0]
	v_pk_fma_f32 v[12:13], v[20:21], v[130:131], v[34:35] op_sel:[0,1,0]
	v_pk_fma_f32 v[36:37], v[14:15], v[124:125], v[36:37] op_sel_hi:[1,0,1]
	v_pk_mul_f32 v[38:39], v[150:151], v[140:141] op_sel:[0,1]
	v_pk_fma_f32 v[14:15], v[20:21], v[132:133], v[36:37] op_sel_hi:[1,0,1]
	v_pk_fma_f32 v[38:39], v[16:17], v[124:125], v[38:39] op_sel:[0,1,0]
	v_pk_mul_f32 v[42:43], v[2:3], v[142:143] op_sel_hi:[1,0]
	v_pk_fma_f32 v[16:17], v[20:21], v[132:133], v[38:39] op_sel:[0,1,0]
	v_pk_mul_f32 v[44:45], v[10:11], v[146:147] op_sel_hi:[1,0]
	v_pk_fma_f32 v[42:43], v[4:5], v[142:143], v[42:43] op_sel:[0,1,0]
	v_pk_fma_f32 v[44:45], v[12:13], v[146:147], v[44:45] op_sel:[0,1,0]
	v_pk_fma_f32 v[42:43], v[6:7], v[144:145], v[42:43] op_sel_hi:[1,0,1]
	v_pk_fma_f32 v[44:45], v[14:15], v[148:149], v[44:45] op_sel_hi:[1,0,1]
	v_pk_fma_f32 v[42:43], v[8:9], v[144:145], v[42:43] op_sel:[0,1,0]
	v_pk_fma_f32 v[44:45], v[16:17], v[148:149], v[44:45] op_sel:[0,1,0]
	v_pk_add_f32 v[42:43], v[42:43], v[44:45]
	ds_read_b128 v[110:113], v180 offset:7424
	ds_read_b128 v[114:117], v180 offset:7440
	ds_read_b64 v[150:151], v181 offset:23808
	ds_read_b128 v[134:137], v180 offset:15616
	ds_read_b128 v[138:141], v180 offset:15632
	ds_read_b128 v[118:121], v180 offset:3328
	ds_read_b128 v[122:125], v180 offset:3344
	ds_read_b128 v[126:129], v180 offset:11520
	ds_read_b128 v[130:133], v180 offset:11536
	ds_read_b128 v[142:145], v180 offset:19712
	ds_read_b128 v[146:149], v180 offset:19728
	s_waitcnt lgkmcnt(11)
; __device__ __forceinline__ void rwkv_block(KP p, int o, int b, int hd, LAS unsigned char* lds, const bf16_t* P, bf16_t* YB) {
;     ...
;             for (int tt = 0; tt < 16; ++tt) {
;                 const int o8 = tt * 64 + c * 8;
;                 const f32x4 ka = *(const LAS f32x4*)(KK + o8), kb = *(const LAS f32x4*)(KK + o8 + 4);
;                 const f32x4 wa = *(const LAS f32x4*)(Wd + o8), wb = *(const LAS f32x4*)(Wd + o8 + 4);
;                 const f32x4 ba = *(const LAS f32x4*)(BB + o8), bb = *(const LAS f32x4*)(BB + o8 + 4);
;                 const f32x4 ma = *(const LAS f32x4*)(KM + o8), mb = *(const LAS f32x4*)(KM + o8 + 4);
;                 const f32x4 ra = *(const LAS f32x4*)(Rr + o8), rb = *(const LAS f32x4*)(Rr + o8 + 4);
;                 const f32x2 v01 = *(const LAS f32x2*)(Vv + tt * 64 + 2 * rp);
;                 const f32x2 k2[4] = {{ka[0], ka[1]}, {ka[2], ka[3]}, {kb[0], kb[1]}, {kb[2], kb[3]}};
;                 const f32x2 w2[4] = {{wa[0], wa[1]}, {wa[2], wa[3]}, {wb[0], wb[1]}, {wb[2], wb[3]}};
;                 const f32x2 b2[4] = {{ba[0], ba[1]}, {ba[2], ba[3]}, {bb[0], bb[1]}, {bb[2], bb[3]}};
;                 const f32x2 m2[4] = {{ma[0], ma[1]}, {ma[2], ma[3]}, {mb[0], mb[1]}, {mb[2], mb[3]}};
;                 const f32x2 r2[4] = {{ra[0], ra[1]}, {ra[2], ra[3]}, {rb[0], rb[1]}, {rb[2], rb[3]}};
;                 f32x2 accA = s[0][0] * k2[0], accB = s[1][0] * k2[0], accA2 = s[0][2] * k2[2], accB2 = s[1][2] * k2[2];
;                 accA = s[0][1] * k2[1] + accA; accB = s[1][1] * k2[1] + accB; accA2 = s[0][3] * k2[3] + accA2; accB2 = s[1][3] * k2[3] + accB2;
;                 accA = accA + accA2; accB = accB + accB2;
;                 float sa0 = accA.x + accA.y, sa1 = accB.x + accB.y;
;                 sa0 += dpp_f<0xB1>(sa0); sa1 += dpp_f<0xB1>(sa1);
;                 sa0 += dpp_f<0x4E>(sa0); sa1 += dpp_f<0x4E>(sa1);
;                 sa0 += dpp_f<0x141>(sa0); sa1 += dpp_f<0x141>(sa1);
;                 const f32x2 saA = {sa0, sa0}, saB = {sa1, sa1}, vA = {v01.x, v01.x}, vB = {v01.y, v01.y};
;                 f32x2 yA, yB;
; #pragma unroll
;                 for (int j = 0; j < 4; ++j) {
;                     f32x2 tA = vA * m2[j], tB = vB * m2[j];
;                     tA = saA * b2[j] + tA; tB = saB * b2[j] + tB;
;                     s[0][j] = s[0][j] * w2[j] + tA; s[1][j] = s[1][j] * w2[j] + tB;
	v_pk_mul_f32 v[20:21], v[2:3], v[64:65] op_sel_hi:[1,0]
	v_pk_mul_f32 v[22:23], v[10:11], v[68:69] op_sel_hi:[1,0]
	v_pk_fma_f32 v[20:21], v[4:5], v[64:65], v[20:21] op_sel:[0,1,0]
	v_pk_fma_f32 v[22:23], v[12:13], v[68:69], v[22:23] op_sel:[0,1,0]
	v_pk_fma_f32 v[20:21], v[6:7], v[66:67], v[20:21] op_sel_hi:[1,0,1]
	v_pk_fma_f32 v[22:23], v[14:15], v[70:71], v[22:23] op_sel_hi:[1,0,1]
	v_pk_fma_f32 v[20:21], v[8:9], v[66:67], v[20:21] op_sel:[0,1,0]
	v_pk_fma_f32 v[22:23], v[16:17], v[70:71], v[22:23] op_sel:[0,1,0]
	v_add_f32_dpp v42, v42, v42 quad_perm:[1,0,3,2] row_mask:0xf bank_mask:0xf bound_ctrl:1
	v_pk_add_f32 v[20:21], v[20:21], v[22:23]
	v_add_f32_dpp v43, v43, v43 quad_perm:[1,0,3,2] row_mask:0xf bank_mask:0xf bound_ctrl:1
	v_add_f32_dpp v42, v42, v42 quad_perm:[2,3,0,1] row_mask:0xf bank_mask:0xf bound_ctrl:1
	v_pk_mul_f32 v[24:25], v[104:105], v[88:89] op_sel_hi:[1,0]
	v_add_f32_dpp v43, v43, v43 quad_perm:[2,3,0,1] row_mask:0xf bank_mask:0xf bound_ctrl:1
	v_add_f32_dpp v42, v42, v42 row_half_mirror row_mask:0xf bank_mask:0xf bound_ctrl:1
	v_pk_fma_f32 v[24:25], v[2:3], v[72:73], v[24:25] op_sel_hi:[1,0,1]
	v_add_f32_dpp v43, v43, v43 row_half_mirror row_mask:0xf bank_mask:0xf bound_ctrl:1
	v_pk_mul_f32 v[26:27], v[104:105], v[88:89] op_sel:[0,1]
	s_mov_b64 exec, vcc
	ds_write_b64 v181, v[42:43] offset:31488
	s_mov_b64 exec, s[12:13]
	v_pk_fma_f32 v[26:27], v[4:5], v[72:73], v[26:27] op_sel:[0,1,0]
	v_pk_mul_f32 v[28:29], v[104:105], v[90:91] op_sel_hi:[1,0]
	v_pk_mul_f32 v[30:31], v[104:105], v[90:91] op_sel:[0,1]
	v_pk_fma_f32 v[28:29], v[6:7], v[74:75], v[28:29] op_sel_hi:[1,0,1]
	v_pk_fma_f32 v[30:31], v[8:9], v[74:75], v[30:31] op_sel:[0,1,0]
	v_add_f32_dpp v20, v20, v20 quad_perm:[1,0,3,2] row_mask:0xf bank_mask:0xf bound_ctrl:1
	v_add_f32_dpp v21, v21, v21 quad_perm:[1,0,3,2] row_mask:0xf bank_mask:0xf bound_ctrl:1
	v_pk_mul_f32 v[32:33], v[104:105], v[92:93] op_sel_hi:[1,0]
	v_add_f32_dpp v20, v20, v20 quad_perm:[2,3,0,1] row_mask:0xf bank_mask:0xf bound_ctrl:1
	v_add_f32_dpp v21, v21, v21 quad_perm:[2,3,0,1] row_mask:0xf bank_mask:0xf bound_ctrl:1
	v_pk_fma_f32 v[32:33], v[10:11], v[76:77], v[32:33] op_sel_hi:[1,0,1]
	v_add_f32_dpp v20, v20, v20 row_half_mirror row_mask:0xf bank_mask:0xf bound_ctrl:1
	v_add_f32_dpp v21, v21, v21 row_half_mirror row_mask:0xf bank_mask:0xf bound_ctrl:1
	v_pk_mul_f32 v[34:35], v[104:105], v[92:93] op_sel:[0,1]
	v_pk_fma_f32 v[2:3], v[20:21], v[80:81], v[24:25] op_sel_hi:[1,0,1]
	v_pk_fma_f32 v[10:11], v[20:21], v[84:85], v[32:33] op_sel_hi:[1,0,1]
	v_pk_fma_f32 v[4:5], v[20:21], v[80:81], v[26:27] op_sel:[0,1,0]
	v_pk_fma_f32 v[6:7], v[20:21], v[82:83], v[28:29] op_sel_hi:[1,0,1]
	v_pk_fma_f32 v[8:9], v[20:21], v[82:83], v[30:31] op_sel:[0,1,0]
	v_pk_fma_f32 v[34:35], v[12:13], v[76:77], v[34:35] op_sel:[0,1,0]
	v_pk_mul_f32 v[36:37], v[104:105], v[94:95] op_sel_hi:[1,0]
	v_pk_fma_f32 v[12:13], v[20:21], v[84:85], v[34:35] op_sel:[0,1,0]
	v_pk_fma_f32 v[36:37], v[14:15], v[78:79], v[36:37] op_sel_hi:[1,0,1]
	v_pk_mul_f32 v[38:39], v[104:105], v[94:95] op_sel:[0,1]
	v_pk_fma_f32 v[14:15], v[20:21], v[86:87], v[36:37] op_sel_hi:[1,0,1]
	v_pk_fma_f32 v[38:39], v[16:17], v[78:79], v[38:39] op_sel:[0,1,0]
	v_pk_mul_f32 v[40:41], v[2:3], v[96:97] op_sel_hi:[1,0]
	v_pk_fma_f32 v[16:17], v[20:21], v[86:87], v[38:39] op_sel:[0,1,0]
	v_pk_mul_f32 v[44:45], v[10:11], v[100:101] op_sel_hi:[1,0]
	v_pk_fma_f32 v[40:41], v[4:5], v[96:97], v[40:41] op_sel:[0,1,0]
	v_pk_fma_f32 v[44:45], v[12:13], v[100:101], v[44:45] op_sel:[0,1,0]
	v_pk_fma_f32 v[40:41], v[6:7], v[98:99], v[40:41] op_sel_hi:[1,0,1]
	v_pk_fma_f32 v[44:45], v[14:15], v[102:103], v[44:45] op_sel_hi:[1,0,1]
	v_pk_fma_f32 v[40:41], v[8:9], v[98:99], v[40:41] op_sel:[0,1,0]
	v_pk_fma_f32 v[44:45], v[16:17], v[102:103], v[44:45] op_sel:[0,1,0]
	v_pk_add_f32 v[40:41], v[40:41], v[44:45]
	ds_read_b128 v[64:67], v180 offset:7680
	ds_read_b128 v[68:71], v180 offset:7696
	ds_read_b64 v[104:105], v181 offset:24064
	ds_read_b128 v[88:91], v180 offset:15872
	ds_read_b128 v[92:95], v180 offset:15888
	ds_read_b128 v[72:75], v180 offset:3584
	ds_read_b128 v[76:79], v180 offset:3600
	ds_read_b128 v[80:83], v180 offset:11776
	ds_read_b128 v[84:87], v180 offset:11792
	ds_read_b128 v[96:99], v180 offset:19968
	ds_read_b128 v[100:103], v180 offset:19984
	s_waitcnt lgkmcnt(11)
; __device__ __forceinline__ void rwkv_block(KP p, int o, int b, int hd, LAS unsigned char* lds, const bf16_t* P, bf16_t* YB) {
;     ...
;             for (int tt = 0; tt < 16; ++tt) {
;                 const int o8 = tt * 64 + c * 8;
;                 const f32x4 ka = *(const LAS f32x4*)(KK + o8), kb = *(const LAS f32x4*)(KK + o8 + 4);
;                 const f32x4 wa = *(const LAS f32x4*)(Wd + o8), wb = *(const LAS f32x4*)(Wd + o8 + 4);
;                 const f32x4 ba = *(const LAS f32x4*)(BB + o8), bb = *(const LAS f32x4*)(BB + o8 + 4);
;                 const f32x4 ma = *(const LAS f32x4*)(KM + o8), mb = *(const LAS f32x4*)(KM + o8 + 4);
;                 const f32x4 ra = *(const LAS f32x4*)(Rr + o8), rb = *(const LAS f32x4*)(Rr + o8 + 4);
;                 const f32x2 v01 = *(const LAS f32x2*)(Vv + tt * 64 + 2 * rp);
;                 const f32x2 k2[4] = {{ka[0], ka[1]}, {ka[2], ka[3]}, {kb[0], kb[1]}, {kb[2], kb[3]}};
;                 const f32x2 w2[4] = {{wa[0], wa[1]}, {wa[2], wa[3]}, {wb[0], wb[1]}, {wb[2], wb[3]}};
;                 const f32x2 b2[4] = {{ba[0], ba[1]}, {ba[2], ba[3]}, {bb[0], bb[1]}, {bb[2], bb[3]}};
;                 const f32x2 m2[4] = {{ma[0], ma[1]}, {ma[2], ma[3]}, {mb[0], mb[1]}, {mb[2], mb[3]}};
;                 const f32x2 r2[4] = {{ra[0], ra[1]}, {ra[2], ra[3]}, {rb[0], rb[1]}, {rb[2], rb[3]}};
;                 f32x2 accA = s[0][0] * k2[0], accB = s[1][0] * k2[0], accA2 = s[0][2] * k2[2], accB2 = s[1][2] * k2[2];
;                 accA = s[0][1] * k2[1] + accA; accB = s[1][1] * k2[1] + accB; accA2 = s[0][3] * k2[3] + accA2; accB2 = s[1][3] * k2[3] + accB2;
;                 accA = accA + accA2; accB = accB + accB2;
;                 float sa0 = accA.x + accA.y, sa1 = accB.x + accB.y;
;                 sa0 += dpp_f<0xB1>(sa0); sa1 += dpp_f<0xB1>(sa1);
;                 sa0 += dpp_f<0x4E>(sa0); sa1 += dpp_f<0x4E>(sa1);
;                 sa0 += dpp_f<0x141>(sa0); sa1 += dpp_f<0x141>(sa1);
;                 const f32x2 saA = {sa0, sa0}, saB = {sa1, sa1}, vA = {v01.x, v01.x}, vB = {v01.y, v01.y};
;                 f32x2 yA, yB;
; #pragma unroll
;                 for (int j = 0; j < 4; ++j) {
;                     f32x2 tA = vA * m2[j], tB = vB * m2[j];
;                     tA = saA * b2[j] + tA; tB = saB * b2[j] + tB;
;                     s[0][j] = s[0][j] * w2[j] + tA; s[1][j] = s[1][j] * w2[j] + tB;
	v_pk_mul_f32 v[20:21], v[2:3], v[110:111] op_sel_hi:[1,0]
	v_pk_mul_f32 v[22:23], v[10:11], v[114:115] op_sel_hi:[1,0]
	v_pk_fma_f32 v[20:21], v[4:5], v[110:111], v[20:21] op_sel:[0,1,0]
	v_pk_fma_f32 v[22:23], v[12:13], v[114:115], v[22:23] op_sel:[0,1,0]
	v_pk_fma_f32 v[20:21], v[6:7], v[112:113], v[20:21] op_sel_hi:[1,0,1]
	v_pk_fma_f32 v[22:23], v[14:15], v[116:117], v[22:23] op_sel_hi:[1,0,1]
	v_pk_fma_f32 v[20:21], v[8:9], v[112:113], v[20:21] op_sel:[0,1,0]
	v_pk_fma_f32 v[22:23], v[16:17], v[116:117], v[22:23] op_sel:[0,1,0]
	v_add_f32_dpp v40, v40, v40 quad_perm:[1,0,3,2] row_mask:0xf bank_mask:0xf bound_ctrl:1
	v_pk_add_f32 v[20:21], v[20:21], v[22:23]
	v_add_f32_dpp v41, v41, v41 quad_perm:[1,0,3,2] row_mask:0xf bank_mask:0xf bound_ctrl:1
	v_add_f32_dpp v40, v40, v40 quad_perm:[2,3,0,1] row_mask:0xf bank_mask:0xf bound_ctrl:1
	v_pk_mul_f32 v[24:25], v[150:151], v[134:135] op_sel_hi:[1,0]
	v_add_f32_dpp v41, v41, v41 quad_perm:[2,3,0,1] row_mask:0xf bank_mask:0xf bound_ctrl:1
	v_add_f32_dpp v40, v40, v40 row_half_mirror row_mask:0xf bank_mask:0xf bound_ctrl:1
	v_pk_fma_f32 v[24:25], v[2:3], v[118:119], v[24:25] op_sel_hi:[1,0,1]
	v_add_f32_dpp v41, v41, v41 row_half_mirror row_mask:0xf bank_mask:0xf bound_ctrl:1
	v_pk_mul_f32 v[26:27], v[150:151], v[134:135] op_sel:[0,1]
	s_mov_b64 exec, vcc
	ds_write_b64 v181, v[40:41] offset:31744
	s_mov_b64 exec, s[12:13]
	v_pk_fma_f32 v[26:27], v[4:5], v[118:119], v[26:27] op_sel:[0,1,0]
	v_pk_mul_f32 v[28:29], v[150:151], v[136:137] op_sel_hi:[1,0]
	v_pk_mul_f32 v[30:31], v[150:151], v[136:137] op_sel:[0,1]
	v_pk_fma_f32 v[28:29], v[6:7], v[120:121], v[28:29] op_sel_hi:[1,0,1]
	v_pk_fma_f32 v[30:31], v[8:9], v[120:121], v[30:31] op_sel:[0,1,0]
	v_add_f32_dpp v20, v20, v20 quad_perm:[1,0,3,2] row_mask:0xf bank_mask:0xf bound_ctrl:1
	v_add_f32_dpp v21, v21, v21 quad_perm:[1,0,3,2] row_mask:0xf bank_mask:0xf bound_ctrl:1
	v_pk_mul_f32 v[32:33], v[150:151], v[138:139] op_sel_hi:[1,0]
	v_add_f32_dpp v20, v20, v20 quad_perm:[2,3,0,1] row_mask:0xf bank_mask:0xf bound_ctrl:1
	v_add_f32_dpp v21, v21, v21 quad_perm:[2,3,0,1] row_mask:0xf bank_mask:0xf bound_ctrl:1
	v_pk_fma_f32 v[32:33], v[10:11], v[122:123], v[32:33] op_sel_hi:[1,0,1]
	v_add_f32_dpp v20, v20, v20 row_half_mirror row_mask:0xf bank_mask:0xf bound_ctrl:1
	v_add_f32_dpp v21, v21, v21 row_half_mirror row_mask:0xf bank_mask:0xf bound_ctrl:1
	v_pk_mul_f32 v[34:35], v[150:151], v[138:139] op_sel:[0,1]
	v_pk_fma_f32 v[2:3], v[20:21], v[126:127], v[24:25] op_sel_hi:[1,0,1]
	v_pk_fma_f32 v[10:11], v[20:21], v[130:131], v[32:33] op_sel_hi:[1,0,1]
	v_pk_fma_f32 v[4:5], v[20:21], v[126:127], v[26:27] op_sel:[0,1,0]
	v_pk_fma_f32 v[6:7], v[20:21], v[128:129], v[28:29] op_sel_hi:[1,0,1]
	v_pk_fma_f32 v[8:9], v[20:21], v[128:129], v[30:31] op_sel:[0,1,0]
	v_pk_fma_f32 v[34:35], v[12:13], v[122:123], v[34:35] op_sel:[0,1,0]
	v_pk_mul_f32 v[36:37], v[150:151], v[140:141] op_sel_hi:[1,0]
	v_pk_fma_f32 v[12:13], v[20:21], v[130:131], v[34:35] op_sel:[0,1,0]
	v_pk_fma_f32 v[36:37], v[14:15], v[124:125], v[36:37] op_sel_hi:[1,0,1]
	v_pk_mul_f32 v[38:39], v[150:151], v[140:141] op_sel:[0,1]
	v_pk_fma_f32 v[14:15], v[20:21], v[132:133], v[36:37] op_sel_hi:[1,0,1]
	v_pk_fma_f32 v[38:39], v[16:17], v[124:125], v[38:39] op_sel:[0,1,0]
	v_pk_mul_f32 v[42:43], v[2:3], v[142:143] op_sel_hi:[1,0]
	v_pk_fma_f32 v[16:17], v[20:21], v[132:133], v[38:39] op_sel:[0,1,0]
	v_pk_mul_f32 v[44:45], v[10:11], v[146:147] op_sel_hi:[1,0]
	v_pk_fma_f32 v[42:43], v[4:5], v[142:143], v[42:43] op_sel:[0,1,0]
	v_pk_fma_f32 v[44:45], v[12:13], v[146:147], v[44:45] op_sel:[0,1,0]
	v_pk_fma_f32 v[42:43], v[6:7], v[144:145], v[42:43] op_sel_hi:[1,0,1]
	v_pk_fma_f32 v[44:45], v[14:15], v[148:149], v[44:45] op_sel_hi:[1,0,1]
	v_pk_fma_f32 v[42:43], v[8:9], v[144:145], v[42:43] op_sel:[0,1,0]
	v_pk_fma_f32 v[44:45], v[16:17], v[148:149], v[44:45] op_sel:[0,1,0]
	v_pk_add_f32 v[42:43], v[42:43], v[44:45]
	ds_read_b128 v[110:113], v180 offset:7936
	ds_read_b128 v[114:117], v180 offset:7952
	ds_read_b64 v[150:151], v181 offset:24320
	ds_read_b128 v[134:137], v180 offset:16128
	ds_read_b128 v[138:141], v180 offset:16144
	ds_read_b128 v[118:121], v180 offset:3840
	ds_read_b128 v[122:125], v180 offset:3856
	ds_read_b128 v[126:129], v180 offset:12032
	ds_read_b128 v[130:133], v180 offset:12048
	ds_read_b128 v[142:145], v180 offset:20224
	ds_read_b128 v[146:149], v180 offset:20240
	s_waitcnt lgkmcnt(11)
; __device__ __forceinline__ void rwkv_block(KP p, int o, int b, int hd, LAS unsigned char* lds, const bf16_t* P, bf16_t* YB) {
;     ...
;             for (int tt = 0; tt < 16; ++tt) {
;                 const int o8 = tt * 64 + c * 8;
;                 const f32x4 ka = *(const LAS f32x4*)(KK + o8), kb = *(const LAS f32x4*)(KK + o8 + 4);
;                 const f32x4 wa = *(const LAS f32x4*)(Wd + o8), wb = *(const LAS f32x4*)(Wd + o8 + 4);
;                 const f32x4 ba = *(const LAS f32x4*)(BB + o8), bb = *(const LAS f32x4*)(BB + o8 + 4);
;                 const f32x4 ma = *(const LAS f32x4*)(KM + o8), mb = *(const LAS f32x4*)(KM + o8 + 4);
;                 const f32x4 ra = *(const LAS f32x4*)(Rr + o8), rb = *(const LAS f32x4*)(Rr + o8 + 4);
;                 const f32x2 v01 = *(const LAS f32x2*)(Vv + tt * 64 + 2 * rp);
;                 const f32x2 k2[4] = {{ka[0], ka[1]}, {ka[2], ka[3]}, {kb[0], kb[1]}, {kb[2], kb[3]}};
;                 const f32x2 w2[4] = {{wa[0], wa[1]}, {wa[2], wa[3]}, {wb[0], wb[1]}, {wb[2], wb[3]}};
;                 const f32x2 b2[4] = {{ba[0], ba[1]}, {ba[2], ba[3]}, {bb[0], bb[1]}, {bb[2], bb[3]}};
;                 const f32x2 m2[4] = {{ma[0], ma[1]}, {ma[2], ma[3]}, {mb[0], mb[1]}, {mb[2], mb[3]}};
;                 const f32x2 r2[4] = {{ra[0], ra[1]}, {ra[2], ra[3]}, {rb[0], rb[1]}, {rb[2], rb[3]}};
;                 f32x2 accA = s[0][0] * k2[0], accB = s[1][0] * k2[0], accA2 = s[0][2] * k2[2], accB2 = s[1][2] * k2[2];
;                 accA = s[0][1] * k2[1] + accA; accB = s[1][1] * k2[1] + accB; accA2 = s[0][3] * k2[3] + accA2; accB2 = s[1][3] * k2[3] + accB2;
;                 accA = accA + accA2; accB = accB + accB2;
;                 float sa0 = accA.x + accA.y, sa1 = accB.x + accB.y;
;                 sa0 += dpp_f<0xB1>(sa0); sa1 += dpp_f<0xB1>(sa1);
;                 sa0 += dpp_f<0x4E>(sa0); sa1 += dpp_f<0x4E>(sa1);
;                 sa0 += dpp_f<0x141>(sa0); sa1 += dpp_f<0x141>(sa1);
;                 const f32x2 saA = {sa0, sa0}, saB = {sa1, sa1}, vA = {v01.x, v01.x}, vB = {v01.y, v01.y};
;                 f32x2 yA, yB;
; #pragma unroll
;                 for (int j = 0; j < 4; ++j) {
;                     f32x2 tA = vA * m2[j], tB = vB * m2[j];
;                     tA = saA * b2[j] + tA; tB = saB * b2[j] + tB;
;                     s[0][j] = s[0][j] * w2[j] + tA; s[1][j] = s[1][j] * w2[j] + tB;
	v_pk_mul_f32 v[20:21], v[2:3], v[64:65] op_sel_hi:[1,0]
	v_pk_mul_f32 v[22:23], v[10:11], v[68:69] op_sel_hi:[1,0]
	v_pk_fma_f32 v[20:21], v[4:5], v[64:65], v[20:21] op_sel:[0,1,0]
	v_pk_fma_f32 v[22:23], v[12:13], v[68:69], v[22:23] op_sel:[0,1,0]
	v_pk_fma_f32 v[20:21], v[6:7], v[66:67], v[20:21] op_sel_hi:[1,0,1]
	v_pk_fma_f32 v[22:23], v[14:15], v[70:71], v[22:23] op_sel_hi:[1,0,1]
	v_pk_fma_f32 v[20:21], v[8:9], v[66:67], v[20:21] op_sel:[0,1,0]
	v_pk_fma_f32 v[22:23], v[16:17], v[70:71], v[22:23] op_sel:[0,1,0]
	v_add_f32_dpp v42, v42, v42 quad_perm:[1,0,3,2] row_mask:0xf bank_mask:0xf bound_ctrl:1
	v_pk_add_f32 v[20:21], v[20:21], v[22:23]
	v_add_f32_dpp v43, v43, v43 quad_perm:[1,0,3,2] row_mask:0xf bank_mask:0xf bound_ctrl:1
	v_add_f32_dpp v42, v42, v42 quad_perm:[2,3,0,1] row_mask:0xf bank_mask:0xf bound_ctrl:1
	v_pk_mul_f32 v[24:25], v[104:105], v[88:89] op_sel_hi:[1,0]
	v_add_f32_dpp v43, v43, v43 quad_perm:[2,3,0,1] row_mask:0xf bank_mask:0xf bound_ctrl:1
	v_add_f32_dpp v42, v42, v42 row_half_mirror row_mask:0xf bank_mask:0xf bound_ctrl:1
	v_pk_fma_f32 v[24:25], v[2:3], v[72:73], v[24:25] op_sel_hi:[1,0,1]
	v_add_f32_dpp v43, v43, v43 row_half_mirror row_mask:0xf bank_mask:0xf bound_ctrl:1
	v_pk_mul_f32 v[26:27], v[104:105], v[88:89] op_sel:[0,1]
	s_mov_b64 exec, vcc
	ds_write_b64 v181, v[42:43] offset:32000
	s_mov_b64 exec, s[12:13]
	v_pk_fma_f32 v[26:27], v[4:5], v[72:73], v[26:27] op_sel:[0,1,0]
	v_pk_mul_f32 v[28:29], v[104:105], v[90:91] op_sel_hi:[1,0]
	v_pk_mul_f32 v[30:31], v[104:105], v[90:91] op_sel:[0,1]
	v_pk_fma_f32 v[28:29], v[6:7], v[74:75], v[28:29] op_sel_hi:[1,0,1]
	v_pk_fma_f32 v[30:31], v[8:9], v[74:75], v[30:31] op_sel:[0,1,0]
	v_add_f32_dpp v20, v20, v20 quad_perm:[1,0,3,2] row_mask:0xf bank_mask:0xf bound_ctrl:1
	v_add_f32_dpp v21, v21, v21 quad_perm:[1,0,3,2] row_mask:0xf bank_mask:0xf bound_ctrl:1
	v_pk_mul_f32 v[32:33], v[104:105], v[92:93] op_sel_hi:[1,0]
	v_add_f32_dpp v20, v20, v20 quad_perm:[2,3,0,1] row_mask:0xf bank_mask:0xf bound_ctrl:1
	v_add_f32_dpp v21, v21, v21 quad_perm:[2,3,0,1] row_mask:0xf bank_mask:0xf bound_ctrl:1
	v_pk_fma_f32 v[32:33], v[10:11], v[76:77], v[32:33] op_sel_hi:[1,0,1]
	v_add_f32_dpp v20, v20, v20 row_half_mirror row_mask:0xf bank_mask:0xf bound_ctrl:1
	v_add_f32_dpp v21, v21, v21 row_half_mirror row_mask:0xf bank_mask:0xf bound_ctrl:1
	v_pk_mul_f32 v[34:35], v[104:105], v[92:93] op_sel:[0,1]
	v_pk_fma_f32 v[2:3], v[20:21], v[80:81], v[24:25] op_sel_hi:[1,0,1]
	v_pk_fma_f32 v[10:11], v[20:21], v[84:85], v[32:33] op_sel_hi:[1,0,1]
	v_pk_fma_f32 v[4:5], v[20:21], v[80:81], v[26:27] op_sel:[0,1,0]
	v_pk_fma_f32 v[6:7], v[20:21], v[82:83], v[28:29] op_sel_hi:[1,0,1]
	v_pk_fma_f32 v[8:9], v[20:21], v[82:83], v[30:31] op_sel:[0,1,0]
	v_pk_fma_f32 v[34:35], v[12:13], v[76:77], v[34:35] op_sel:[0,1,0]
	v_pk_mul_f32 v[36:37], v[104:105], v[94:95] op_sel_hi:[1,0]
	v_pk_fma_f32 v[12:13], v[20:21], v[84:85], v[34:35] op_sel:[0,1,0]
	v_pk_fma_f32 v[36:37], v[14:15], v[78:79], v[36:37] op_sel_hi:[1,0,1]
	v_pk_mul_f32 v[38:39], v[104:105], v[94:95] op_sel:[0,1]
	v_pk_fma_f32 v[14:15], v[20:21], v[86:87], v[36:37] op_sel_hi:[1,0,1]
	v_pk_fma_f32 v[38:39], v[16:17], v[78:79], v[38:39] op_sel:[0,1,0]
	v_pk_mul_f32 v[40:41], v[2:3], v[96:97] op_sel_hi:[1,0]
	v_pk_fma_f32 v[16:17], v[20:21], v[86:87], v[38:39] op_sel:[0,1,0]
	v_pk_mul_f32 v[44:45], v[10:11], v[100:101] op_sel_hi:[1,0]
	v_pk_fma_f32 v[40:41], v[4:5], v[96:97], v[40:41] op_sel:[0,1,0]
	v_pk_fma_f32 v[44:45], v[12:13], v[100:101], v[44:45] op_sel:[0,1,0]
	v_pk_fma_f32 v[40:41], v[6:7], v[98:99], v[40:41] op_sel_hi:[1,0,1]
	v_pk_fma_f32 v[44:45], v[14:15], v[102:103], v[44:45] op_sel_hi:[1,0,1]
	v_pk_fma_f32 v[40:41], v[8:9], v[98:99], v[40:41] op_sel:[0,1,0]
	v_pk_fma_f32 v[44:45], v[16:17], v[102:103], v[44:45] op_sel:[0,1,0]
	v_pk_add_f32 v[40:41], v[40:41], v[44:45]
	s_waitcnt lgkmcnt(0)
; __device__ __forceinline__ void rwkv_block(KP p, int o, int b, int hd, LAS unsigned char* lds, const bf16_t* P, bf16_t* YB) {
;     ...
;             for (int tt = 0; tt < 16; ++tt) {
;                 const int o8 = tt * 64 + c * 8;
;                 const f32x4 ka = *(const LAS f32x4*)(KK + o8), kb = *(const LAS f32x4*)(KK + o8 + 4);
;                 const f32x4 wa = *(const LAS f32x4*)(Wd + o8), wb = *(const LAS f32x4*)(Wd + o8 + 4);
;                 const f32x4 ba = *(const LAS f32x4*)(BB + o8), bb = *(const LAS f32x4*)(BB + o8 + 4);
;                 const f32x4 ma = *(const LAS f32x4*)(KM + o8), mb = *(const LAS f32x4*)(KM + o8 + 4);
;                 const f32x4 ra = *(const LAS f32x4*)(Rr + o8), rb = *(const LAS f32x4*)(Rr + o8 + 4);
;                 const f32x2 v01 = *(const LAS f32x2*)(Vv + tt * 64 + 2 * rp);
;                 const f32x2 k2[4] = {{ka[0], ka[1]}, {ka[2], ka[3]}, {kb[0], kb[1]}, {kb[2], kb[3]}};
;                 const f32x2 w2[4] = {{wa[0], wa[1]}, {wa[2], wa[3]}, {wb[0], wb[1]}, {wb[2], wb[3]}};
;                 const f32x2 b2[4] = {{ba[0], ba[1]}, {ba[2], ba[3]}, {bb[0], bb[1]}, {bb[2], bb[3]}};
;                 const f32x2 m2[4] = {{ma[0], ma[1]}, {ma[2], ma[3]}, {mb[0], mb[1]}, {mb[2], mb[3]}};
;                 const f32x2 r2[4] = {{ra[0], ra[1]}, {ra[2], ra[3]}, {rb[0], rb[1]}, {rb[2], rb[3]}};
;                 f32x2 accA = s[0][0] * k2[0], accB = s[1][0] * k2[0], accA2 = s[0][2] * k2[2], accB2 = s[1][2] * k2[2];
;                 accA = s[0][1] * k2[1] + accA; accB = s[1][1] * k2[1] + accB; accA2 = s[0][3] * k2[3] + accA2; accB2 = s[1][3] * k2[3] + accB2;
;                 accA = accA + accA2; accB = accB + accB2;
;                 float sa0 = accA.x + accA.y, sa1 = accB.x + accB.y;
;                 sa0 += dpp_f<0xB1>(sa0); sa1 += dpp_f<0xB1>(sa1);
;                 sa0 += dpp_f<0x4E>(sa0); sa1 += dpp_f<0x4E>(sa1);
;                 sa0 += dpp_f<0x141>(sa0); sa1 += dpp_f<0x141>(sa1);
;                 const f32x2 saA = {sa0, sa0}, saB = {sa1, sa1}, vA = {v01.x, v01.x}, vB = {v01.y, v01.y};
;                 f32x2 yA, yB;
; #pragma unroll
;                 for (int j = 0; j < 4; ++j) {
;                     f32x2 tA = vA * m2[j], tB = vB * m2[j];
;                     tA = saA * b2[j] + tA; tB = saB * b2[j] + tB;
;                     s[0][j] = s[0][j] * w2[j] + tA; s[1][j] = s[1][j] * w2[j] + tB;
	v_pk_mul_f32 v[20:21], v[2:3], v[110:111] op_sel_hi:[1,0]
	v_pk_mul_f32 v[22:23], v[10:11], v[114:115] op_sel_hi:[1,0]
	v_pk_fma_f32 v[20:21], v[4:5], v[110:111], v[20:21] op_sel:[0,1,0]
	v_pk_fma_f32 v[22:23], v[12:13], v[114:115], v[22:23] op_sel:[0,1,0]
	v_pk_fma_f32 v[20:21], v[6:7], v[112:113], v[20:21] op_sel_hi:[1,0,1]
	v_pk_fma_f32 v[22:23], v[14:15], v[116:117], v[22:23] op_sel_hi:[1,0,1]
	v_pk_fma_f32 v[20:21], v[8:9], v[112:113], v[20:21] op_sel:[0,1,0]
	v_pk_fma_f32 v[22:23], v[16:17], v[116:117], v[22:23] op_sel:[0,1,0]
	v_add_f32_dpp v40, v40, v40 quad_perm:[1,0,3,2] row_mask:0xf bank_mask:0xf bound_ctrl:1
	v_pk_add_f32 v[20:21], v[20:21], v[22:23]
	v_add_f32_dpp v41, v41, v41 quad_perm:[1,0,3,2] row_mask:0xf bank_mask:0xf bound_ctrl:1
	v_add_f32_dpp v40, v40, v40 quad_perm:[2,3,0,1] row_mask:0xf bank_mask:0xf bound_ctrl:1
	v_pk_mul_f32 v[24:25], v[150:151], v[134:135] op_sel_hi:[1,0]
	v_add_f32_dpp v41, v41, v41 quad_perm:[2,3,0,1] row_mask:0xf bank_mask:0xf bound_ctrl:1
	v_add_f32_dpp v40, v40, v40 row_half_mirror row_mask:0xf bank_mask:0xf bound_ctrl:1
	v_pk_fma_f32 v[24:25], v[2:3], v[118:119], v[24:25] op_sel_hi:[1,0,1]
	v_add_f32_dpp v41, v41, v41 row_half_mirror row_mask:0xf bank_mask:0xf bound_ctrl:1
	v_pk_mul_f32 v[26:27], v[150:151], v[134:135] op_sel:[0,1]
	s_mov_b64 exec, vcc
	ds_write_b64 v181, v[40:41] offset:32256
	s_mov_b64 exec, s[12:13]
	v_pk_fma_f32 v[26:27], v[4:5], v[118:119], v[26:27] op_sel:[0,1,0]
	v_pk_mul_f32 v[28:29], v[150:151], v[136:137] op_sel_hi:[1,0]
	v_pk_mul_f32 v[30:31], v[150:151], v[136:137] op_sel:[0,1]
	v_pk_fma_f32 v[28:29], v[6:7], v[120:121], v[28:29] op_sel_hi:[1,0,1]
	v_pk_fma_f32 v[30:31], v[8:9], v[120:121], v[30:31] op_sel:[0,1,0]
	v_add_f32_dpp v20, v20, v20 quad_perm:[1,0,3,2] row_mask:0xf bank_mask:0xf bound_ctrl:1
	v_add_f32_dpp v21, v21, v21 quad_perm:[1,0,3,2] row_mask:0xf bank_mask:0xf bound_ctrl:1
	v_pk_mul_f32 v[32:33], v[150:151], v[138:139] op_sel_hi:[1,0]
	v_add_f32_dpp v20, v20, v20 quad_perm:[2,3,0,1] row_mask:0xf bank_mask:0xf bound_ctrl:1
	v_add_f32_dpp v21, v21, v21 quad_perm:[2,3,0,1] row_mask:0xf bank_mask:0xf bound_ctrl:1
	v_pk_fma_f32 v[32:33], v[10:11], v[122:123], v[32:33] op_sel_hi:[1,0,1]
	v_add_f32_dpp v20, v20, v20 row_half_mirror row_mask:0xf bank_mask:0xf bound_ctrl:1
	v_add_f32_dpp v21, v21, v21 row_half_mirror row_mask:0xf bank_mask:0xf bound_ctrl:1
	v_pk_mul_f32 v[34:35], v[150:151], v[138:139] op_sel:[0,1]
	v_pk_fma_f32 v[2:3], v[20:21], v[126:127], v[24:25] op_sel_hi:[1,0,1]
	v_pk_fma_f32 v[10:11], v[20:21], v[130:131], v[32:33] op_sel_hi:[1,0,1]
	v_pk_fma_f32 v[4:5], v[20:21], v[126:127], v[26:27] op_sel:[0,1,0]
	v_pk_fma_f32 v[6:7], v[20:21], v[128:129], v[28:29] op_sel_hi:[1,0,1]
	v_pk_fma_f32 v[8:9], v[20:21], v[128:129], v[30:31] op_sel:[0,1,0]
	v_pk_fma_f32 v[34:35], v[12:13], v[122:123], v[34:35] op_sel:[0,1,0]
	v_pk_mul_f32 v[36:37], v[150:151], v[140:141] op_sel_hi:[1,0]
	v_pk_fma_f32 v[12:13], v[20:21], v[130:131], v[34:35] op_sel:[0,1,0]
	v_pk_fma_f32 v[36:37], v[14:15], v[124:125], v[36:37] op_sel_hi:[1,0,1]
	v_pk_mul_f32 v[38:39], v[150:151], v[140:141] op_sel:[0,1]
	v_pk_fma_f32 v[14:15], v[20:21], v[132:133], v[36:37] op_sel_hi:[1,0,1]
	v_pk_fma_f32 v[38:39], v[16:17], v[124:125], v[38:39] op_sel:[0,1,0]
	v_pk_mul_f32 v[42:43], v[2:3], v[142:143] op_sel_hi:[1,0]
	v_pk_fma_f32 v[16:17], v[20:21], v[132:133], v[38:39] op_sel:[0,1,0]
	v_pk_mul_f32 v[44:45], v[10:11], v[146:147] op_sel_hi:[1,0]
	v_pk_fma_f32 v[42:43], v[4:5], v[142:143], v[42:43] op_sel:[0,1,0]
	v_pk_fma_f32 v[44:45], v[12:13], v[146:147], v[44:45] op_sel:[0,1,0]
	v_pk_fma_f32 v[42:43], v[6:7], v[144:145], v[42:43] op_sel_hi:[1,0,1]
	v_pk_fma_f32 v[44:45], v[14:15], v[148:149], v[44:45] op_sel_hi:[1,0,1]
	v_pk_fma_f32 v[42:43], v[8:9], v[144:145], v[42:43] op_sel:[0,1,0]
	v_pk_fma_f32 v[44:45], v[16:17], v[148:149], v[44:45] op_sel:[0,1,0]
	v_pk_add_f32 v[42:43], v[42:43], v[44:45]
	s_nop 1
	v_add_f32_dpp v42, v42, v42 quad_perm:[1,0,3,2] row_mask:0xf bank_mask:0xf bound_ctrl:1
	v_add_f32_dpp v43, v43, v43 quad_perm:[1,0,3,2] row_mask:0xf bank_mask:0xf bound_ctrl:1
	s_nop 0
	v_add_f32_dpp v42, v42, v42 quad_perm:[2,3,0,1] row_mask:0xf bank_mask:0xf bound_ctrl:1
	v_add_f32_dpp v43, v43, v43 quad_perm:[2,3,0,1] row_mask:0xf bank_mask:0xf bound_ctrl:1
	s_nop 0
	v_add_f32_dpp v42, v42, v42 row_half_mirror row_mask:0xf bank_mask:0xf bound_ctrl:1
	v_add_f32_dpp v43, v43, v43 row_half_mirror row_mask:0xf bank_mask:0xf bound_ctrl:1
	s_mov_b64 exec, vcc
	ds_write_b64 v181, v[42:43] offset:32512
	s_mov_b64 exec, s[12:13]
	s_waitcnt lgkmcnt(0)
	s_barrier
	s_add_i32 s1, s1, 1
	s_cmpk_eq_i32 s1, 0x100
	s_cbranch_scc0 .Lrk_scan_loop
	s_setprio 0
	s_branch .LBB0_156
